# speedup vs baseline: 1.0701x; 1.0592x over previous
; __device__ __forceinline__ void gemm_phase(KP p, char* shmc, const u16* __restrict__ A,
;                                            const u16* __restrict__ Bt, const int N, const int K, const int mode,
;                                            const float* __restrict__ xin, const float resw) {
;     ...
;   const int nM = S_ / BM, nN = N / BM, nwg = nM * nN;
;   const int nt = K / BK;
.LBB0_44:
	s_andn2_b64 vcc, exec, s[6:7]
	s_cbranch_vccnz .LBB0_316
	s_lshr_b32 s6, s50, 6
	s_add_i32 s56, s6, -1
	s_add_i32 s67, s6, -2
	s_lshl_b32 s8, s50, 6
	s_lshl_b64 s[6:7], s[56:57], 7
	s_add_u32 s56, s12, s6
	s_addc_u32 s80, s13, s7
	s_lshl_b32 s81, s22, 2
	v_cvt_f32_u32_e32 v0, s81
	s_lshl_b32 s68, s22, 3
	s_waitcnt lgkmcnt(0)
	s_cmp_lg_u64 s[20:21], 0
	s_cselect_b64 s[22:23], -1, 0
	v_rcp_iflag_f32_e32 v0, v0
	s_sub_i32 s6, 0, s81
	s_mov_b32 s19, s18
	s_mov_b32 s90, 0
	v_mul_f32_e32 v0, 0x4f7ffffe, v0
	v_cvt_u32_f32_e32 v0, v0
	s_lshl_b32 s72, s8, 1
	v_readfirstlane_b32 s7, v0
	s_mul_i32 s6, s6, s7
	s_mul_hi_u32 s6, s7, s6
	s_add_i32 s69, s7, s6
	s_mov_b32 s100, 1
	s_branch .LBB0_47

; #define STAGE(P, BASE, br, kt) do { const u16* _gb = (BASE) + ((size_t)(br) * K + (size_t)(kt) * BK); \
;     __builtin_amdgcn_global_load_lds((const unsigned*)(_gb + goff0), (unsigned*)((char*)(P) + tid * 16), 16, 0, 0); \
;     __builtin_amdgcn_global_load_lds((const unsigned*)(_gb + (size_t)64 * K + goff0), (unsigned*)((char*)(P) + tid * 16 + 8192), 16, 0, 0); } while (0)
; #define LDA(dst, b, h) _Pragma("unroll") for (int m = 0; m < 4; ++m) _Pragma("unroll") for (int k = 0; k < 2; ++k) \
;     dst[m][k] = *reinterpret_cast<const bf16x8*>((char*)SA(b, h) + lds_byte(wr * 64 + m * 16 + fr, k * 32 + fq * 8))
; #define LDB(dst, b, h) _Pragma("unroll") for (int n = 0; n < 2; ++n) _Pragma("unroll") for (int k = 0; k < 2; ++k) \
;     dst[n][k] = *reinterpret_cast<const bf16x8*>((char*)SB(b, h) + lds_byte(wc * 32 + n * 16 + fr, k * 32 + fq * 8))
; #define WAIT_V(n) asm volatile("s_waitcnt vmcnt(" #n ")" ::: "memory")
; #define BAR __builtin_amdgcn_s_barrier()
; #define SCHED __builtin_amdgcn_sched_barrier(0)
; __device__ __forceinline__ void gemm_phase(KP p, char* shmc, const u16* __restrict__ A,
;                                            const u16* __restrict__ Bt, const int N, const int K, const int mode,
;                                            const float* __restrict__ xin, const float resw) {
;     ...
;   while (tix < nwg) {
;     int tid = threadIdx.x;
;     asm volatile("" : "+v"(tid));
;     const int wid = tid >> 6, lane = tid & 63, wr = wid >> 2, wc = wid & 3, fr = lane & 15, fq = lane >> 4;
;     int goff0;
;     { int r_, c_; stage_rc(tid * 16, r_, c_); goff0 = r_ * K + c_; }
;     f32x4 acc[2][2][4][2];
; #pragma unroll
;     for (int a = 0; a < 2; ++a)
; #pragma unroll
;       for (int b = 0; b < 2; ++b)
; #pragma unroll
;         for (int m = 0; m < 4; ++m)
; #pragma unroll
;           for (int n = 0; n < 2; ++n) acc[a][b][m][n] = f32x4{0.f, 0.f, 0.f, 0.f};
;     bf16x8 At[4][2], B0[2][2], B1[2][2];
;     WAIT_V(0);
;     if (wr == 1) BAR;
;     BAR;
;     for (int t = 0; t < nt - 2; t += 2) {
;       LDB(B0, 0, 0); SCHED; LDA(At, 0, 0); STAGE(SA(1, 1), A, brow + HALF, t + 1);
.LBB0_47:
	v_mov_b32_e32 v217, v210
	s_waitcnt vmcnt(0)
	s_nop 0
	v_ashrrev_i32_e32 v0, 8, v217
	v_bfe_i32 v2, v217, 27, 1
	v_lshlrev_b32_e32 v135, 4, v217
	v_lshrrev_b32_e32 v2, 22, v2
	s_add_i32 s6, s24, 0x80
	v_add_u32_e32 v2, v135, v2
	s_mul_hi_i32 s7, s6, s50
	s_mul_i32 s6, s6, s50
	v_and_b32_e32 v2, 0xfffffc00, v2
	s_lshl_b64 s[6:7], s[6:7], 1
	v_sub_u32_e32 v2, v135, v2
	s_add_u32 s8, s12, s6
	s_mul_hi_i32 s27, s28, s50
	s_mul_i32 s26, s28, s50
	v_ashrrev_i32_e32 v1, 31, v217
	v_lshrrev_b32_e32 v3, 4, v2
	s_addc_u32 s9, s13, s7
	s_ashr_i32 s29, s28, 31
	s_lshl_b64 s[26:27], s[26:27], 1
	v_lshrrev_b32_e32 v1, 26, v1
	v_bitop3_b32 v2, v3, v2, 32 bitop3:0x6c
	s_add_u32 s26, s14, s26
	s_mul_hi_i32 s31, s24, s50
	s_mul_i32 s30, s24, s50
	v_add_u32_e32 v1, v217, v1
	v_ashrrev_i32_e32 v4, 31, v2
	s_addc_u32 s27, s15, s27
	s_ashr_i32 s25, s24, 31
	s_lshl_b64 s[30:31], s[30:31], 1
	v_ashrrev_i32_e32 v1, 6, v1
	v_lshrrev_b32_e32 v4, 26, v4
	s_add_u32 s36, s12, s30
	v_lshlrev_b32_e32 v3, 3, v1
	v_add_u32_e32 v4, v2, v4
	s_addc_u32 s37, s13, s31
	s_add_i32 s30, s28, 0x80
	v_and_b32_e32 v3, -16, v3
	v_ashrrev_i32_e32 v5, 6, v4
	s_mul_hi_i32 s31, s30, s50
	s_mul_i32 s30, s30, s50
	v_add_u32_e32 v3, v5, v3
	s_lshl_b64 s[30:31], s[30:31], 1
	v_mul_lo_u32 v138, v3, s50
	v_and_b32_e32 v3, 48, v217
	s_add_u32 s38, s14, s30
	v_lshlrev_b32_e32 v8, 6, v217
	s_movk_i32 s30, 0x3c0
	s_addc_u32 s39, s15, s31
	v_lshlrev_b32_e32 v10, 13, v0
	v_and_or_b32 v0, v8, s30, v3
	s_lshl_b64 s[30:31], s[28:29], 1
	s_add_u32 s40, s30, 0x80
	s_addc_u32 s41, s31, 0
	s_mul_i32 s41, s50, s41
	s_mul_hi_u32 s42, s50, s40
	s_add_i32 s42, s42, s41
	s_mul_i32 s40, s50, s40
	s_add_u32 s40, s14, s40
	s_addc_u32 s41, s15, s42
	s_lshl_b64 s[46:47], s[24:25], 1
	s_add_u32 s42, s46, 0x80
	s_addc_u32 s43, s47, 0
	s_mul_i32 s43, s50, s43
	s_mul_hi_u32 s44, s50, s42
	s_add_i32 s44, s44, s43
	s_mul_i32 s42, s50, s42
	s_add_u32 s42, s12, s42
	s_addc_u32 s43, s13, s44
	s_add_u32 s44, s30, 0x180
	s_addc_u32 s45, s31, 0
	v_lshlrev_b32_e32 v1, 5, v1
	s_mul_i32 s45, s50, s45
	s_mul_hi_u32 vcc_lo, s50, s44
	v_and_b32_e32 v137, 32, v1
	v_and_b32_e32 v1, 0xc0, v4
	s_add_i32 vcc_lo, vcc_lo, s45
	s_mul_i32 s44, s50, s44
	v_sub_u32_e32 v1, v2, v1
	s_add_u32 s44, s14, s44
	v_ashrrev_i16_sdwa v1, v212, sext(v1) dst_sel:DWORD dst_unused:UNUSED_PAD src0_sel:DWORD src1_sel:BYTE_0
	v_and_b32_e32 v2, 15, v217
	s_addc_u32 s45, s15, vcc_lo
	v_bfe_i32 v139, v1, 0, 16
	v_lshlrev_b32_e32 v1, 6, v2
	v_lshlrev_b32_e32 v2, 2, v217
	s_add_u32 s46, s46, 0x180
	v_and_b32_e32 v2, 32, v2
	s_addc_u32 s47, s47, 0
	v_bitop3_b32 v1, v1, v2, v3 bitop3:0x36
	v_xad_u32 v2, v0, v2, 0
	v_add3_u32 v0, v138, v137, v139
	s_mul_i32 s47, s50, s47
	s_mul_hi_u32 vcc_lo, s50, s46
	v_add_u32_e32 v4, s83, v1
	v_add_u32_e32 v5, s84, v1
	v_add_u32_e32 v6, s85, v1
	v_add_u32_e32 v7, s86, v1
	v_add_u32_e32 v11, 0, v1
	v_ashrrev_i32_e32 v1, 31, v0
	s_add_i32 vcc_lo, vcc_lo, s47
	s_mul_i32 s46, s50, s46
	v_and_b32_e32 v9, 0x3000, v8
	v_or_b32_e32 v3, 0x800, v10
	v_or_b32_e32 v8, 0x1000, v10
	v_or_b32_e32 v12, 0x1800, v10
	s_waitcnt lgkmcnt(0)
	v_lshlrev_b64 v[128:129], 1, v[0:1]
	s_add_u32 s46, s12, s46
	v_mov_b32_e32 v0, 0
	s_addc_u32 s47, s13, vcc_lo
	s_mov_b32 vcc_lo, 0
	v_add_u32_e32 v141, v4, v9
	v_add_u32_e32 v133, v11, v10
	v_add_u32_e32 v132, v2, v3
	v_add_u32_e32 v131, v2, v8
	v_add_u32_e32 v130, v2, v12
	v_add_u32_e32 v140, v5, v9
	v_add_u32_e32 v136, v6, v9
	v_add_u32_e32 v134, v7, v9
	v_mov_b32_e32 v234, v133
	v_mov_b32_e32 v235, v141
	v_mov_b32_e32 v236, v128
	v_add_u32_e32 v237, s72, v128
	v_lshrrev_b32_e32 v238, 6, v210
	v_lshlrev_b32_e32 v238, 10, v238
	s_lshr_b32 s41, s50, 7
	s_add_i32 s41, s41, -2
	v_readfirstlane_b32 s40, v238
	s_add_u32 s8, s8, 0x80
	s_addc_u32 s9, s9, 0
	s_cmp_eq_u32 s100, 0
	s_cbranch_scc1 .Lmy_noextra
	s_add_u32 m0, s40, 0xc000
	s_nop 0
	global_load_lds_dwordx4 v236, s[8:9]
	s_add_u32 m0, s40, 0xe000
	s_nop 0
	global_load_lds_dwordx4 v237, s[8:9]
	s_mov_b32 s100, 0
.Lmy_noextra:
	s_add_u32 s8, s8, 0x80
	s_addc_u32 s9, s9, 0
	s_add_u32 s36, s36, 0x100
	s_addc_u32 s37, s37, 0
	s_add_u32 s26, s26, 0x100
	s_addc_u32 s27, s27, 0
	s_add_u32 s38, s38, 0x100
	s_addc_u32 s39, s39, 0
	v_mov_b32_e32 v1, v0
	v_mov_b32_e32 v2, v0
	v_mov_b32_e32 v3, v0
	v_mov_b32_e32 v4, v0
	v_mov_b32_e32 v5, v0
	v_mov_b32_e32 v6, v0
	v_mov_b32_e32 v7, v0
	v_mov_b32_e32 v8, v0
	v_mov_b32_e32 v9, v0
	v_mov_b32_e32 v10, v0
	v_mov_b32_e32 v11, v0
	v_mov_b32_e32 v12, v0
	v_mov_b32_e32 v13, v0
	v_mov_b32_e32 v14, v0
	v_mov_b32_e32 v15, v0
	v_mov_b32_e32 v16, v0
	v_mov_b32_e32 v17, v0
	v_mov_b32_e32 v18, v0
	v_mov_b32_e32 v19, v0
	v_mov_b32_e32 v20, v0
	v_mov_b32_e32 v21, v0
	v_mov_b32_e32 v22, v0
	v_mov_b32_e32 v23, v0
	v_mov_b32_e32 v24, v0
	v_mov_b32_e32 v25, v0
	v_mov_b32_e32 v26, v0
	v_mov_b32_e32 v27, v0
	v_mov_b32_e32 v28, v0
	v_mov_b32_e32 v29, v0
	v_mov_b32_e32 v30, v0
	v_mov_b32_e32 v31, v0
	v_mov_b32_e32 v32, v0
	v_mov_b32_e32 v33, v0
	v_mov_b32_e32 v34, v0
	v_mov_b32_e32 v35, v0
	v_mov_b32_e32 v36, v0
	v_mov_b32_e32 v37, v0
	v_mov_b32_e32 v38, v0
	v_mov_b32_e32 v39, v0
	v_mov_b32_e32 v40, v0
	v_mov_b32_e32 v41, v0
	v_mov_b32_e32 v42, v0
	v_mov_b32_e32 v43, v0
	v_mov_b32_e32 v44, v0
	v_mov_b32_e32 v45, v0
	v_mov_b32_e32 v46, v0
	v_mov_b32_e32 v47, v0
	v_mov_b32_e32 v48, v0
	v_mov_b32_e32 v49, v0
	v_mov_b32_e32 v50, v0
	v_mov_b32_e32 v51, v0
	v_mov_b32_e32 v52, v0
	v_mov_b32_e32 v53, v0
	v_mov_b32_e32 v54, v0
	v_mov_b32_e32 v55, v0
	v_mov_b32_e32 v56, v0
	v_mov_b32_e32 v57, v0
	v_mov_b32_e32 v58, v0
	v_mov_b32_e32 v59, v0
	v_mov_b32_e32 v60, v0
	v_mov_b32_e32 v61, v0
	v_mov_b32_e32 v62, v0
	v_mov_b32_e32 v63, v0
	v_mov_b32_e32 v64, v0
; #define STAGE(P, BASE, br, kt) do { const u16* _gb = (BASE) + ((size_t)(br) * K + (size_t)(kt) * BK); \
;     __builtin_amdgcn_global_load_lds((const unsigned*)(_gb + goff0), (unsigned*)((char*)(P) + tid * 16), 16, 0, 0); \
;     __builtin_amdgcn_global_load_lds((const unsigned*)(_gb + (size_t)64 * K + goff0), (unsigned*)((char*)(P) + tid * 16 + 8192), 16, 0, 0); } while (0)
; #define LDA(dst, b, h) _Pragma("unroll") for (int m = 0; m < 4; ++m) _Pragma("unroll") for (int k = 0; k < 2; ++k) \
;     dst[m][k] = *reinterpret_cast<const bf16x8*>((char*)SA(b, h) + lds_byte(wr * 64 + m * 16 + fr, k * 32 + fq * 8))
; #define LDB(dst, b, h) _Pragma("unroll") for (int n = 0; n < 2; ++n) _Pragma("unroll") for (int k = 0; k < 2; ++k) \
;     dst[n][k] = *reinterpret_cast<const bf16x8*>((char*)SB(b, h) + lds_byte(wc * 32 + n * 16 + fr, k * 32 + fq * 8))
; #define WAIT_V(n) asm volatile("s_waitcnt vmcnt(" #n ")" ::: "memory")
; #define WAIT_L(n) asm volatile("s_waitcnt lgkmcnt(" #n ")" ::: "memory")
; #define BAR __builtin_amdgcn_s_barrier()
; #define SCHED __builtin_amdgcn_sched_barrier(0)
; __device__ __forceinline__ void gemm_phase(KP p, char* shmc, const u16* __restrict__ A,
;                                            const u16* __restrict__ Bt, const int N, const int K, const int mode,
;                                            const float* __restrict__ xin, const float resw) {
;     ...
;     f32x4 acc[2][2][4][2];
; #pragma unroll
;     for (int a = 0; a < 2; ++a)
; #pragma unroll
;       for (int b = 0; b < 2; ++b)
; #pragma unroll
;         for (int m = 0; m < 4; ++m)
; #pragma unroll
;           for (int n = 0; n < 2; ++n) acc[a][b][m][n] = f32x4{0.f, 0.f, 0.f, 0.f};
;     bf16x8 At[4][2], B0[2][2], B1[2][2];
;     WAIT_V(0);
;     if (wr == 1) BAR;
;     BAR;
;     for (int t = 0; t < nt - 2; t += 2) {
;       LDB(B0, 0, 0); SCHED; LDA(At, 0, 0); STAGE(SA(1, 1), A, brow + HALF, t + 1);
;       WAIT_L(8); BAR; WAIT_L(0); MMA(0, 0, At, B0); BAR; SCHED;
;       LDB(B1, 0, 1); STAGE(SB(0, 0), Bt, bcol, t + 2);
;       BAR; WAIT_L(0); MMA(0, 1, At, B1); BAR;
;       LDA(At, 0, 1); STAGE(SA(0, 0), A, brow, t + 2);
;       BAR; WAIT_L(0); MMA(1, 0, At, B0); BAR; SCHED;
;       STAGE(SB(0, 1), Bt, bcol + HALF, t + 2);
;       WAIT_V(6); BAR; MMA(1, 1, At, B1); BAR;
	v_mov_b32_e32 v65, v0
	v_mov_b32_e32 v66, v0
	v_mov_b32_e32 v67, v0
	v_mov_b32_e32 v68, v0
	v_mov_b32_e32 v69, v0
	v_mov_b32_e32 v70, v0
	v_mov_b32_e32 v71, v0
	v_mov_b32_e32 v72, v0
	v_mov_b32_e32 v73, v0
	v_mov_b32_e32 v74, v0
	v_mov_b32_e32 v75, v0
	v_mov_b32_e32 v76, v0
	v_mov_b32_e32 v77, v0
	v_mov_b32_e32 v78, v0
	v_mov_b32_e32 v79, v0
	v_mov_b32_e32 v80, v0
	v_mov_b32_e32 v81, v0
	v_mov_b32_e32 v82, v0
	v_mov_b32_e32 v83, v0
	v_mov_b32_e32 v84, v0
	v_mov_b32_e32 v85, v0
	v_mov_b32_e32 v86, v0
	v_mov_b32_e32 v87, v0
	v_mov_b32_e32 v88, v0
	v_mov_b32_e32 v89, v0
	v_mov_b32_e32 v90, v0
	v_mov_b32_e32 v91, v0
	v_mov_b32_e32 v92, v0
	v_mov_b32_e32 v93, v0
	v_mov_b32_e32 v94, v0
	v_mov_b32_e32 v95, v0
	v_mov_b32_e32 v96, v0
	v_mov_b32_e32 v97, v0
	v_mov_b32_e32 v98, v0
	v_mov_b32_e32 v99, v0
	v_mov_b32_e32 v100, v0
	v_mov_b32_e32 v101, v0
	v_mov_b32_e32 v102, v0
	v_mov_b32_e32 v103, v0
	v_mov_b32_e32 v104, v0
	v_mov_b32_e32 v105, v0
	v_mov_b32_e32 v106, v0
	v_mov_b32_e32 v107, v0
	v_mov_b32_e32 v108, v0
	v_mov_b32_e32 v109, v0
	v_mov_b32_e32 v110, v0
	v_mov_b32_e32 v111, v0
	v_mov_b32_e32 v112, v0
	v_mov_b32_e32 v113, v0
	v_mov_b32_e32 v114, v0
	v_mov_b32_e32 v115, v0
	v_mov_b32_e32 v116, v0
	v_mov_b32_e32 v117, v0
	v_mov_b32_e32 v118, v0
	v_mov_b32_e32 v119, v0
	v_mov_b32_e32 v120, v0
	v_mov_b32_e32 v121, v0
	v_mov_b32_e32 v122, v0
	v_mov_b32_e32 v123, v0
	v_mov_b32_e32 v124, v0
	v_mov_b32_e32 v125, v0
	v_mov_b32_e32 v126, v0
	v_mov_b32_e32 v127, v0
	s_waitcnt vmcnt(0)
	s_barrier
	ds_read_b128 v[194:197], v235 offset:0
	ds_read_b128 v[198:201], v235 offset:1024
	ds_read_b128 v[202:205], v235 offset:2048
	ds_read_b128 v[206:209], v235 offset:3072
	ds_read_b128 v[128:131], v234 offset:0
	ds_read_b128 v[132:135], v234 offset:1024
	ds_read_b128 v[136:139], v234 offset:2048
	ds_read_b128 v[140:143], v234 offset:3072
	ds_read_b128 v[144:147], v234 offset:4096
	ds_read_b128 v[148:151], v234 offset:5120
	ds_read_b128 v[152:155], v234 offset:6144
	ds_read_b128 v[156:159], v234 offset:7168
	s_waitcnt lgkmcnt(0)
	s_barrier
	s_add_u32 m0, s40, 0x0
	s_nop 0
	global_load_lds_dwordx4 v236, s[36:37]
	s_add_u32 m0, s40, 0x2000
	s_nop 0
	global_load_lds_dwordx4 v237, s[36:37]
	s_add_u32 s36, s36, 0x80
	s_addc_u32 s37, s37, 0
.Lmy_kloop:
	s_waitcnt vmcnt(12) lgkmcnt(0)
	s_barrier
	v_mfma_f32_16x16x32_bf16 v[120:123], v[194:197], v[128:131], v[120:123]
	v_mfma_f32_16x16x32_bf16 v[112:115], v[202:205], v[128:131], v[112:115]
	ds_read_b128 v[218:221], v235 offset:16384
	v_mfma_f32_16x16x32_bf16 v[104:107], v[194:197], v[136:139], v[104:107]
	ds_read_b128 v[222:225], v235 offset:17408
	v_mfma_f32_16x16x32_bf16 v[96:99], v[202:205], v[136:139], v[96:99]
	ds_read_b128 v[226:229], v235 offset:18432
	s_add_u32 m0, s40, 0x10000
	v_mfma_f32_16x16x32_bf16 v[88:91], v[194:197], v[144:147], v[88:91]
	ds_read_b128 v[230:233], v235 offset:19456
	v_mfma_f32_16x16x32_bf16 v[80:83], v[202:205], v[144:147], v[80:83]
	global_load_lds_dwordx4 v236, s[26:27]
	v_mfma_f32_16x16x32_bf16 v[72:75], v[194:197], v[152:155], v[72:75]
	v_mfma_f32_16x16x32_bf16 v[64:67], v[202:205], v[152:155], v[64:67]
	s_add_u32 m0, s40, 0x12000
	v_mfma_f32_16x16x32_bf16 v[120:123], v[198:201], v[132:135], v[120:123]
	v_mfma_f32_16x16x32_bf16 v[112:115], v[206:209], v[132:135], v[112:115]
	global_load_lds_dwordx4 v237, s[26:27]
	v_mfma_f32_16x16x32_bf16 v[104:107], v[198:201], v[140:143], v[104:107]
	v_mfma_f32_16x16x32_bf16 v[96:99], v[206:209], v[140:143], v[96:99]
	s_add_u32 s26, s26, 0x80
	s_addc_u32 s27, s27, 0
	v_mfma_f32_16x16x32_bf16 v[88:91], v[198:201], v[148:151], v[88:91]
	v_mfma_f32_16x16x32_bf16 v[80:83], v[206:209], v[148:151], v[80:83]
	v_mfma_f32_16x16x32_bf16 v[72:75], v[198:201], v[156:159], v[72:75]
	v_mfma_f32_16x16x32_bf16 v[64:67], v[206:209], v[156:159], v[64:67]
	s_waitcnt vmcnt(12) lgkmcnt(0)
	s_barrier
	v_mfma_f32_16x16x32_bf16 v[124:127], v[218:221], v[128:131], v[124:127]
	v_mfma_f32_16x16x32_bf16 v[116:119], v[226:229], v[128:131], v[116:119]
	ds_read_b128 v[160:163], v234 offset:16384
	v_mfma_f32_16x16x32_bf16 v[108:111], v[218:221], v[136:139], v[108:111]
	ds_read_b128 v[164:167], v234 offset:17408
	v_mfma_f32_16x16x32_bf16 v[100:103], v[226:229], v[136:139], v[100:103]
	ds_read_b128 v[168:171], v234 offset:18432
	s_add_u32 m0, s40, 0x14000
	v_mfma_f32_16x16x32_bf16 v[92:95], v[218:221], v[144:147], v[92:95]
	ds_read_b128 v[172:175], v234 offset:19456
	v_mfma_f32_16x16x32_bf16 v[84:87], v[226:229], v[144:147], v[84:87]
	ds_read_b128 v[176:179], v234 offset:20480
	global_load_lds_dwordx4 v236, s[38:39]
	v_mfma_f32_16x16x32_bf16 v[76:79], v[218:221], v[152:155], v[76:79]
	ds_read_b128 v[180:183], v234 offset:21504
	v_mfma_f32_16x16x32_bf16 v[68:71], v[226:229], v[152:155], v[68:71]
	ds_read_b128 v[184:187], v234 offset:22528
	s_add_u32 m0, s40, 0x16000
	v_mfma_f32_16x16x32_bf16 v[124:127], v[222:225], v[132:135], v[124:127]
	ds_read_b128 v[188:191], v234 offset:23552
	v_mfma_f32_16x16x32_bf16 v[116:119], v[230:233], v[132:135], v[116:119]
	global_load_lds_dwordx4 v237, s[38:39]
	v_mfma_f32_16x16x32_bf16 v[108:111], v[222:225], v[140:143], v[108:111]
	v_mfma_f32_16x16x32_bf16 v[100:103], v[230:233], v[140:143], v[100:103]
	s_add_u32 s38, s38, 0x80
	s_addc_u32 s39, s39, 0
	v_mfma_f32_16x16x32_bf16 v[92:95], v[222:225], v[148:151], v[92:95]
	v_mfma_f32_16x16x32_bf16 v[84:87], v[230:233], v[148:151], v[84:87]
	v_mfma_f32_16x16x32_bf16 v[76:79], v[222:225], v[156:159], v[76:79]
	v_mfma_f32_16x16x32_bf16 v[68:71], v[230:233], v[156:159], v[68:71]
	s_waitcnt vmcnt(12) lgkmcnt(0)
	s_barrier
; #define STAGE(P, BASE, br, kt) do { const u16* _gb = (BASE) + ((size_t)(br) * K + (size_t)(kt) * BK); \
;     __builtin_amdgcn_global_load_lds((const unsigned*)(_gb + goff0), (unsigned*)((char*)(P) + tid * 16), 16, 0, 0); \
;     __builtin_amdgcn_global_load_lds((const unsigned*)(_gb + (size_t)64 * K + goff0), (unsigned*)((char*)(P) + tid * 16 + 8192), 16, 0, 0); } while (0)
; #define LDA(dst, b, h) _Pragma("unroll") for (int m = 0; m < 4; ++m) _Pragma("unroll") for (int k = 0; k < 2; ++k) \
;     dst[m][k] = *reinterpret_cast<const bf16x8*>((char*)SA(b, h) + lds_byte(wr * 64 + m * 16 + fr, k * 32 + fq * 8))
; #define LDB(dst, b, h) _Pragma("unroll") for (int n = 0; n < 2; ++n) _Pragma("unroll") for (int k = 0; k < 2; ++k) \
;     dst[n][k] = *reinterpret_cast<const bf16x8*>((char*)SB(b, h) + lds_byte(wc * 32 + n * 16 + fr, k * 32 + fq * 8))
; #define MMA(ai, bj, At, Bt_) do { __builtin_amdgcn_s_setprio(1); \
;     _Pragma("unroll") for (int m = 0; m < 4; ++m) _Pragma("unroll") for (int n = 0; n < 2; ++n) _Pragma("unroll") for (int k = 0; k < 2; ++k) \
;       acc[ai][bj][m][n] = __builtin_amdgcn_mfma_f32_16x16x32_bf16(Bt_[n][k], At[m][k], acc[ai][bj][m][n], 0, 0, 0); \
;     __builtin_amdgcn_s_setprio(0); } while (0)
; #define WAIT_V(n) asm volatile("s_waitcnt vmcnt(" #n ")" ::: "memory")
; __device__ __forceinline__ void gemm_phase(KP p, char* shmc, const u16* __restrict__ A,
;                                            const u16* __restrict__ Bt, const int N, const int K, const int mode,
;                                            const float* __restrict__ xin, const float resw) {
;     ...
;       LDB(B1, 0, 1); STAGE(SB(0, 0), Bt, bcol, t + 2);
;       BAR; WAIT_L(0); MMA(0, 1, At, B1); BAR;
;       LDA(At, 0, 1); STAGE(SA(0, 0), A, brow, t + 2);
;       BAR; WAIT_L(0); MMA(1, 0, At, B0); BAR; SCHED;
;       STAGE(SB(0, 1), Bt, bcol + HALF, t + 2);
;       WAIT_V(6); BAR; MMA(1, 1, At, B1); BAR;
;       LDB(B0, 1, 0); SCHED; LDA(At, 1, 0); STAGE(SA(0, 1), A, brow + HALF, t + 2);
;       WAIT_L(8); BAR; WAIT_L(0); MMA(0, 0, At, B0); BAR; SCHED;
;       LDB(B1, 1, 1); STAGE(SB(1, 0), Bt, bcol, t + 3);
;       BAR; WAIT_L(0); MMA(0, 1, At, B1); BAR;
;       LDA(At, 1, 1); STAGE(SA(1, 0), A, brow, t + 3);
;       BAR; WAIT_L(0); MMA(1, 0, At, B0); BAR; SCHED;
;       STAGE(SB(1, 1), Bt, bcol + HALF, t + 3);
;       WAIT_V(6); BAR; MMA(1, 1, At, B1); BAR;
	v_mfma_f32_16x16x32_bf16 v[56:59], v[194:197], v[160:163], v[56:59]
	v_mfma_f32_16x16x32_bf16 v[48:51], v[202:205], v[160:163], v[48:51]
	ds_read_b128 v[128:131], v234 offset:32768
	v_mfma_f32_16x16x32_bf16 v[40:43], v[194:197], v[168:171], v[40:43]
	ds_read_b128 v[132:135], v234 offset:33792
	v_mfma_f32_16x16x32_bf16 v[32:35], v[202:205], v[168:171], v[32:35]
	ds_read_b128 v[136:139], v234 offset:34816
	s_add_u32 m0, s40, 0x4000
	v_mfma_f32_16x16x32_bf16 v[24:27], v[194:197], v[176:179], v[24:27]
	ds_read_b128 v[140:143], v234 offset:35840
	v_mfma_f32_16x16x32_bf16 v[16:19], v[202:205], v[176:179], v[16:19]
	ds_read_b128 v[144:147], v234 offset:36864
	global_load_lds_dwordx4 v236, s[8:9]
	v_mfma_f32_16x16x32_bf16 v[8:11], v[194:197], v[184:187], v[8:11]
	ds_read_b128 v[148:151], v234 offset:37888
	v_mfma_f32_16x16x32_bf16 v[0:3], v[202:205], v[184:187], v[0:3]
	ds_read_b128 v[152:155], v234 offset:38912
	s_add_u32 m0, s40, 0x6000
	v_mfma_f32_16x16x32_bf16 v[56:59], v[198:201], v[164:167], v[56:59]
	ds_read_b128 v[156:159], v234 offset:39936
	v_mfma_f32_16x16x32_bf16 v[48:51], v[206:209], v[164:167], v[48:51]
	global_load_lds_dwordx4 v237, s[8:9]
	v_mfma_f32_16x16x32_bf16 v[40:43], v[198:201], v[172:175], v[40:43]
	v_mfma_f32_16x16x32_bf16 v[32:35], v[206:209], v[172:175], v[32:35]
	s_add_u32 s8, s8, 0x80
	s_addc_u32 s9, s9, 0
	v_mfma_f32_16x16x32_bf16 v[24:27], v[198:201], v[180:183], v[24:27]
	v_mfma_f32_16x16x32_bf16 v[16:19], v[206:209], v[180:183], v[16:19]
	v_mfma_f32_16x16x32_bf16 v[8:11], v[198:201], v[188:191], v[8:11]
	v_mfma_f32_16x16x32_bf16 v[0:3], v[206:209], v[188:191], v[0:3]
	s_waitcnt vmcnt(12) lgkmcnt(0)
	s_barrier
	v_mfma_f32_16x16x32_bf16 v[60:63], v[218:221], v[160:163], v[60:63]
	v_mfma_f32_16x16x32_bf16 v[52:55], v[226:229], v[160:163], v[52:55]
	ds_read_b128 v[194:197], v235 offset:32768
	v_mfma_f32_16x16x32_bf16 v[44:47], v[218:221], v[168:171], v[44:47]
	ds_read_b128 v[198:201], v235 offset:33792
	v_mfma_f32_16x16x32_bf16 v[36:39], v[226:229], v[168:171], v[36:39]
	ds_read_b128 v[202:205], v235 offset:34816
	s_add_u32 m0, s40, 0x8000
	v_mfma_f32_16x16x32_bf16 v[28:31], v[218:221], v[176:179], v[28:31]
	ds_read_b128 v[206:209], v235 offset:35840
	v_mfma_f32_16x16x32_bf16 v[20:23], v[226:229], v[176:179], v[20:23]
	global_load_lds_dwordx4 v236, s[36:37]
	v_mfma_f32_16x16x32_bf16 v[12:15], v[218:221], v[184:187], v[12:15]
	v_mfma_f32_16x16x32_bf16 v[4:7], v[226:229], v[184:187], v[4:7]
	s_add_u32 m0, s40, 0xa000
	v_mfma_f32_16x16x32_bf16 v[60:63], v[222:225], v[164:167], v[60:63]
	v_mfma_f32_16x16x32_bf16 v[52:55], v[230:233], v[164:167], v[52:55]
	global_load_lds_dwordx4 v237, s[36:37]
	v_mfma_f32_16x16x32_bf16 v[44:47], v[222:225], v[172:175], v[44:47]
	v_mfma_f32_16x16x32_bf16 v[36:39], v[230:233], v[172:175], v[36:39]
	s_add_u32 s36, s36, 0x80
	s_addc_u32 s37, s37, 0
	v_mfma_f32_16x16x32_bf16 v[28:31], v[222:225], v[180:183], v[28:31]
	v_mfma_f32_16x16x32_bf16 v[20:23], v[230:233], v[180:183], v[20:23]
	v_mfma_f32_16x16x32_bf16 v[12:15], v[222:225], v[188:191], v[12:15]
	v_mfma_f32_16x16x32_bf16 v[4:7], v[230:233], v[188:191], v[4:7]
	s_waitcnt vmcnt(12) lgkmcnt(0)
	s_barrier
	v_mfma_f32_16x16x32_bf16 v[120:123], v[194:197], v[128:131], v[120:123]
	v_mfma_f32_16x16x32_bf16 v[112:115], v[202:205], v[128:131], v[112:115]
	ds_read_b128 v[218:221], v235 offset:49152
	v_mfma_f32_16x16x32_bf16 v[104:107], v[194:197], v[136:139], v[104:107]
	ds_read_b128 v[222:225], v235 offset:50176
	v_mfma_f32_16x16x32_bf16 v[96:99], v[202:205], v[136:139], v[96:99]
	ds_read_b128 v[226:229], v235 offset:51200
	s_add_u32 m0, s40, 0x18000
	v_mfma_f32_16x16x32_bf16 v[88:91], v[194:197], v[144:147], v[88:91]
	ds_read_b128 v[230:233], v235 offset:52224
	v_mfma_f32_16x16x32_bf16 v[80:83], v[202:205], v[144:147], v[80:83]
	global_load_lds_dwordx4 v236, s[26:27]
	v_mfma_f32_16x16x32_bf16 v[72:75], v[194:197], v[152:155], v[72:75]
	v_mfma_f32_16x16x32_bf16 v[64:67], v[202:205], v[152:155], v[64:67]
	s_add_u32 m0, s40, 0x1a000
	v_mfma_f32_16x16x32_bf16 v[120:123], v[198:201], v[132:135], v[120:123]
	v_mfma_f32_16x16x32_bf16 v[112:115], v[206:209], v[132:135], v[112:115]
	global_load_lds_dwordx4 v237, s[26:27]
	v_mfma_f32_16x16x32_bf16 v[104:107], v[198:201], v[140:143], v[104:107]
	v_mfma_f32_16x16x32_bf16 v[96:99], v[206:209], v[140:143], v[96:99]
	s_add_u32 s26, s26, 0x80
	s_addc_u32 s27, s27, 0
	v_mfma_f32_16x16x32_bf16 v[88:91], v[198:201], v[148:151], v[88:91]
	v_mfma_f32_16x16x32_bf16 v[80:83], v[206:209], v[148:151], v[80:83]
	v_mfma_f32_16x16x32_bf16 v[72:75], v[198:201], v[156:159], v[72:75]
	v_mfma_f32_16x16x32_bf16 v[64:67], v[206:209], v[156:159], v[64:67]
	s_waitcnt vmcnt(12) lgkmcnt(0)
	s_barrier
	v_mfma_f32_16x16x32_bf16 v[124:127], v[218:221], v[128:131], v[124:127]
	v_mfma_f32_16x16x32_bf16 v[116:119], v[226:229], v[128:131], v[116:119]
	ds_read_b128 v[160:163], v234 offset:49152
	v_mfma_f32_16x16x32_bf16 v[108:111], v[218:221], v[136:139], v[108:111]
	ds_read_b128 v[164:167], v234 offset:50176
	v_mfma_f32_16x16x32_bf16 v[100:103], v[226:229], v[136:139], v[100:103]
	ds_read_b128 v[168:171], v234 offset:51200
	s_add_u32 m0, s40, 0x1c000
	v_mfma_f32_16x16x32_bf16 v[92:95], v[218:221], v[144:147], v[92:95]
	ds_read_b128 v[172:175], v234 offset:52224
	v_mfma_f32_16x16x32_bf16 v[84:87], v[226:229], v[144:147], v[84:87]
	ds_read_b128 v[176:179], v234 offset:53248
	global_load_lds_dwordx4 v236, s[38:39]
	v_mfma_f32_16x16x32_bf16 v[76:79], v[218:221], v[152:155], v[76:79]
	ds_read_b128 v[180:183], v234 offset:54272
	v_mfma_f32_16x16x32_bf16 v[68:71], v[226:229], v[152:155], v[68:71]
	ds_read_b128 v[184:187], v234 offset:55296
	s_add_u32 m0, s40, 0x1e000
	v_mfma_f32_16x16x32_bf16 v[124:127], v[222:225], v[132:135], v[124:127]
	ds_read_b128 v[188:191], v234 offset:56320
	v_mfma_f32_16x16x32_bf16 v[116:119], v[230:233], v[132:135], v[116:119]
	global_load_lds_dwordx4 v237, s[38:39]
	v_mfma_f32_16x16x32_bf16 v[108:111], v[222:225], v[140:143], v[108:111]
	v_mfma_f32_16x16x32_bf16 v[100:103], v[230:233], v[140:143], v[100:103]
	s_add_u32 s38, s38, 0x80
	s_addc_u32 s39, s39, 0
	v_mfma_f32_16x16x32_bf16 v[92:95], v[222:225], v[148:151], v[92:95]
	v_mfma_f32_16x16x32_bf16 v[84:87], v[230:233], v[148:151], v[84:87]
	v_mfma_f32_16x16x32_bf16 v[76:79], v[222:225], v[156:159], v[76:79]
	v_mfma_f32_16x16x32_bf16 v[68:71], v[230:233], v[156:159], v[68:71]
	s_waitcnt vmcnt(12) lgkmcnt(0)
	s_barrier
; #define STAGE(P, BASE, br, kt) do { const u16* _gb = (BASE) + ((size_t)(br) * K + (size_t)(kt) * BK); \
;     __builtin_amdgcn_global_load_lds((const unsigned*)(_gb + goff0), (unsigned*)((char*)(P) + tid * 16), 16, 0, 0); \
;     __builtin_amdgcn_global_load_lds((const unsigned*)(_gb + (size_t)64 * K + goff0), (unsigned*)((char*)(P) + tid * 16 + 8192), 16, 0, 0); } while (0)
; #define LDA(dst, b, h) _Pragma("unroll") for (int m = 0; m < 4; ++m) _Pragma("unroll") for (int k = 0; k < 2; ++k) \
;     dst[m][k] = *reinterpret_cast<const bf16x8*>((char*)SA(b, h) + lds_byte(wr * 64 + m * 16 + fr, k * 32 + fq * 8))
; #define LDB(dst, b, h) _Pragma("unroll") for (int n = 0; n < 2; ++n) _Pragma("unroll") for (int k = 0; k < 2; ++k) \
;     dst[n][k] = *reinterpret_cast<const bf16x8*>((char*)SB(b, h) + lds_byte(wc * 32 + n * 16 + fr, k * 32 + fq * 8))
; #define WAIT_V(n) asm volatile("s_waitcnt vmcnt(" #n ")" ::: "memory")
; #define WAIT_L(n) asm volatile("s_waitcnt lgkmcnt(" #n ")" ::: "memory")
; #define BAR __builtin_amdgcn_s_barrier()
; #define SCHED __builtin_amdgcn_sched_barrier(0)
; __device__ __forceinline__ void gemm_phase(KP p, char* shmc, const u16* __restrict__ A,
;                                            const u16* __restrict__ Bt, const int N, const int K, const int mode,
;                                            const float* __restrict__ xin, const float resw) {
;     ...
;     for (int t = 0; t < nt - 2; t += 2) {
;       LDB(B0, 0, 0); SCHED; LDA(At, 0, 0); STAGE(SA(1, 1), A, brow + HALF, t + 1);
;       WAIT_L(8); BAR; WAIT_L(0); MMA(0, 0, At, B0); BAR; SCHED;
;       LDB(B1, 0, 1); STAGE(SB(0, 0), Bt, bcol, t + 2);
;       BAR; WAIT_L(0); MMA(0, 1, At, B1); BAR;
;       LDA(At, 0, 1); STAGE(SA(0, 0), A, brow, t + 2);
;       BAR; WAIT_L(0); MMA(1, 0, At, B0); BAR; SCHED;
;       STAGE(SB(0, 1), Bt, bcol + HALF, t + 2);
;       WAIT_V(6); BAR; MMA(1, 1, At, B1); BAR;
;       LDB(B0, 1, 0); SCHED; LDA(At, 1, 0); STAGE(SA(0, 1), A, brow + HALF, t + 2);
;       WAIT_L(8); BAR; WAIT_L(0); MMA(0, 0, At, B0); BAR; SCHED;
;       LDB(B1, 1, 1); STAGE(SB(1, 0), Bt, bcol, t + 3);
;       BAR; WAIT_L(0); MMA(0, 1, At, B1); BAR;
;       LDA(At, 1, 1); STAGE(SA(1, 0), A, brow, t + 3);
;       BAR; WAIT_L(0); MMA(1, 0, At, B0); BAR; SCHED;
;       STAGE(SB(1, 1), Bt, bcol + HALF, t + 3);
;       WAIT_V(6); BAR; MMA(1, 1, At, B1); BAR;
;     }
	v_mfma_f32_16x16x32_bf16 v[56:59], v[194:197], v[160:163], v[56:59]
	v_mfma_f32_16x16x32_bf16 v[48:51], v[202:205], v[160:163], v[48:51]
	ds_read_b128 v[128:131], v234 offset:0
	v_mfma_f32_16x16x32_bf16 v[40:43], v[194:197], v[168:171], v[40:43]
	ds_read_b128 v[132:135], v234 offset:1024
	v_mfma_f32_16x16x32_bf16 v[32:35], v[202:205], v[168:171], v[32:35]
	ds_read_b128 v[136:139], v234 offset:2048
	s_add_u32 m0, s40, 0xc000
	v_mfma_f32_16x16x32_bf16 v[24:27], v[194:197], v[176:179], v[24:27]
	ds_read_b128 v[140:143], v234 offset:3072
	v_mfma_f32_16x16x32_bf16 v[16:19], v[202:205], v[176:179], v[16:19]
	ds_read_b128 v[144:147], v234 offset:4096
	global_load_lds_dwordx4 v236, s[8:9]
	v_mfma_f32_16x16x32_bf16 v[8:11], v[194:197], v[184:187], v[8:11]
	ds_read_b128 v[148:151], v234 offset:5120
	v_mfma_f32_16x16x32_bf16 v[0:3], v[202:205], v[184:187], v[0:3]
	ds_read_b128 v[152:155], v234 offset:6144
	s_add_u32 m0, s40, 0xe000
	v_mfma_f32_16x16x32_bf16 v[56:59], v[198:201], v[164:167], v[56:59]
	ds_read_b128 v[156:159], v234 offset:7168
	v_mfma_f32_16x16x32_bf16 v[48:51], v[206:209], v[164:167], v[48:51]
	global_load_lds_dwordx4 v237, s[8:9]
	v_mfma_f32_16x16x32_bf16 v[40:43], v[198:201], v[172:175], v[40:43]
	v_mfma_f32_16x16x32_bf16 v[32:35], v[206:209], v[172:175], v[32:35]
	s_add_u32 s8, s8, 0x80
	s_addc_u32 s9, s9, 0
	v_mfma_f32_16x16x32_bf16 v[24:27], v[198:201], v[180:183], v[24:27]
	v_mfma_f32_16x16x32_bf16 v[16:19], v[206:209], v[180:183], v[16:19]
	v_mfma_f32_16x16x32_bf16 v[8:11], v[198:201], v[188:191], v[8:11]
	v_mfma_f32_16x16x32_bf16 v[0:3], v[206:209], v[188:191], v[0:3]
	s_waitcnt vmcnt(12) lgkmcnt(0)
	s_barrier
	v_mfma_f32_16x16x32_bf16 v[60:63], v[218:221], v[160:163], v[60:63]
	v_mfma_f32_16x16x32_bf16 v[52:55], v[226:229], v[160:163], v[52:55]
	ds_read_b128 v[194:197], v235 offset:0
	v_mfma_f32_16x16x32_bf16 v[44:47], v[218:221], v[168:171], v[44:47]
	ds_read_b128 v[198:201], v235 offset:1024
	v_mfma_f32_16x16x32_bf16 v[36:39], v[226:229], v[168:171], v[36:39]
	ds_read_b128 v[202:205], v235 offset:2048
	s_add_u32 m0, s40, 0x0
	v_mfma_f32_16x16x32_bf16 v[28:31], v[218:221], v[176:179], v[28:31]
	ds_read_b128 v[206:209], v235 offset:3072
	v_mfma_f32_16x16x32_bf16 v[20:23], v[226:229], v[176:179], v[20:23]
	global_load_lds_dwordx4 v236, s[36:37]
	v_mfma_f32_16x16x32_bf16 v[12:15], v[218:221], v[184:187], v[12:15]
	v_mfma_f32_16x16x32_bf16 v[4:7], v[226:229], v[184:187], v[4:7]
	s_add_u32 m0, s40, 0x2000
	v_mfma_f32_16x16x32_bf16 v[60:63], v[222:225], v[164:167], v[60:63]
	v_mfma_f32_16x16x32_bf16 v[52:55], v[230:233], v[164:167], v[52:55]
	global_load_lds_dwordx4 v237, s[36:37]
	v_mfma_f32_16x16x32_bf16 v[44:47], v[222:225], v[172:175], v[44:47]
	v_mfma_f32_16x16x32_bf16 v[36:39], v[230:233], v[172:175], v[36:39]
	s_add_u32 s36, s36, 0x80
	s_addc_u32 s37, s37, 0
	v_mfma_f32_16x16x32_bf16 v[28:31], v[222:225], v[180:183], v[28:31]
	v_mfma_f32_16x16x32_bf16 v[20:23], v[230:233], v[180:183], v[20:23]
	v_mfma_f32_16x16x32_bf16 v[12:15], v[222:225], v[188:191], v[12:15]
	v_mfma_f32_16x16x32_bf16 v[4:7], v[230:233], v[188:191], v[4:7]
	s_add_i32 s41, s41, -1
	s_cmp_lg_u32 s41, 0
	s_cbranch_scc1 .Lmy_kloop
	s_waitcnt vmcnt(12) lgkmcnt(0)
	s_barrier
	v_mfma_f32_16x16x32_bf16 v[120:123], v[194:197], v[128:131], v[120:123]
	v_mfma_f32_16x16x32_bf16 v[112:115], v[202:205], v[128:131], v[112:115]
	ds_read_b128 v[218:221], v235 offset:16384
	v_mfma_f32_16x16x32_bf16 v[104:107], v[194:197], v[136:139], v[104:107]
	ds_read_b128 v[222:225], v235 offset:17408
	v_mfma_f32_16x16x32_bf16 v[96:99], v[202:205], v[136:139], v[96:99]
	ds_read_b128 v[226:229], v235 offset:18432
	s_add_u32 m0, s40, 0x10000
	v_mfma_f32_16x16x32_bf16 v[88:91], v[194:197], v[144:147], v[88:91]
	ds_read_b128 v[230:233], v235 offset:19456
	v_mfma_f32_16x16x32_bf16 v[80:83], v[202:205], v[144:147], v[80:83]
	global_load_lds_dwordx4 v236, s[26:27]
	v_mfma_f32_16x16x32_bf16 v[72:75], v[194:197], v[152:155], v[72:75]
	v_mfma_f32_16x16x32_bf16 v[64:67], v[202:205], v[152:155], v[64:67]
	s_add_u32 m0, s40, 0x12000
	v_mfma_f32_16x16x32_bf16 v[120:123], v[198:201], v[132:135], v[120:123]
	v_mfma_f32_16x16x32_bf16 v[112:115], v[206:209], v[132:135], v[112:115]
	global_load_lds_dwordx4 v237, s[26:27]
	v_mfma_f32_16x16x32_bf16 v[104:107], v[198:201], v[140:143], v[104:107]
	v_mfma_f32_16x16x32_bf16 v[96:99], v[206:209], v[140:143], v[96:99]
	s_add_u32 s26, s26, 0x80
	s_addc_u32 s27, s27, 0
	v_mfma_f32_16x16x32_bf16 v[88:91], v[198:201], v[148:151], v[88:91]
	v_mfma_f32_16x16x32_bf16 v[80:83], v[206:209], v[148:151], v[80:83]
	v_mfma_f32_16x16x32_bf16 v[72:75], v[198:201], v[156:159], v[72:75]
	v_mfma_f32_16x16x32_bf16 v[64:67], v[206:209], v[156:159], v[64:67]
	s_waitcnt vmcnt(12) lgkmcnt(0)
	s_barrier
	v_mfma_f32_16x16x32_bf16 v[124:127], v[218:221], v[128:131], v[124:127]
	v_mfma_f32_16x16x32_bf16 v[116:119], v[226:229], v[128:131], v[116:119]
	ds_read_b128 v[160:163], v234 offset:16384
	v_mfma_f32_16x16x32_bf16 v[108:111], v[218:221], v[136:139], v[108:111]
	ds_read_b128 v[164:167], v234 offset:17408
	v_mfma_f32_16x16x32_bf16 v[100:103], v[226:229], v[136:139], v[100:103]
	ds_read_b128 v[168:171], v234 offset:18432
	s_add_u32 m0, s40, 0x14000
	v_mfma_f32_16x16x32_bf16 v[92:95], v[218:221], v[144:147], v[92:95]
	ds_read_b128 v[172:175], v234 offset:19456
	v_mfma_f32_16x16x32_bf16 v[84:87], v[226:229], v[144:147], v[84:87]
	ds_read_b128 v[176:179], v234 offset:20480
	global_load_lds_dwordx4 v236, s[38:39]
	v_mfma_f32_16x16x32_bf16 v[76:79], v[218:221], v[152:155], v[76:79]
	ds_read_b128 v[180:183], v234 offset:21504
	v_mfma_f32_16x16x32_bf16 v[68:71], v[226:229], v[152:155], v[68:71]
	ds_read_b128 v[184:187], v234 offset:22528
	s_add_u32 m0, s40, 0x16000
	v_mfma_f32_16x16x32_bf16 v[124:127], v[222:225], v[132:135], v[124:127]
	ds_read_b128 v[188:191], v234 offset:23552
	v_mfma_f32_16x16x32_bf16 v[116:119], v[230:233], v[132:135], v[116:119]
	global_load_lds_dwordx4 v237, s[38:39]
	v_mfma_f32_16x16x32_bf16 v[108:111], v[222:225], v[140:143], v[108:111]
	v_mfma_f32_16x16x32_bf16 v[100:103], v[230:233], v[140:143], v[100:103]
	s_add_u32 s38, s38, 0x80
	s_addc_u32 s39, s39, 0
	v_mfma_f32_16x16x32_bf16 v[92:95], v[222:225], v[148:151], v[92:95]
	v_mfma_f32_16x16x32_bf16 v[84:87], v[230:233], v[148:151], v[84:87]
	v_mfma_f32_16x16x32_bf16 v[76:79], v[222:225], v[156:159], v[76:79]
	v_mfma_f32_16x16x32_bf16 v[68:71], v[230:233], v[156:159], v[68:71]
	s_waitcnt vmcnt(12) lgkmcnt(0)
	s_barrier
; #define STAGE(P, BASE, br, kt) do { const u16* _gb = (BASE) + ((size_t)(br) * K + (size_t)(kt) * BK); \
;     __builtin_amdgcn_global_load_lds((const unsigned*)(_gb + goff0), (unsigned*)((char*)(P) + tid * 16), 16, 0, 0); \
;     __builtin_amdgcn_global_load_lds((const unsigned*)(_gb + (size_t)64 * K + goff0), (unsigned*)((char*)(P) + tid * 16 + 8192), 16, 0, 0); } while (0)
; #define LDA(dst, b, h) _Pragma("unroll") for (int m = 0; m < 4; ++m) _Pragma("unroll") for (int k = 0; k < 2; ++k) \
;     dst[m][k] = *reinterpret_cast<const bf16x8*>((char*)SA(b, h) + lds_byte(wr * 64 + m * 16 + fr, k * 32 + fq * 8))
; #define LDB(dst, b, h) _Pragma("unroll") for (int n = 0; n < 2; ++n) _Pragma("unroll") for (int k = 0; k < 2; ++k) \
;     dst[n][k] = *reinterpret_cast<const bf16x8*>((char*)SB(b, h) + lds_byte(wc * 32 + n * 16 + fr, k * 32 + fq * 8))
; #define MMA(ai, bj, At, Bt_) do { __builtin_amdgcn_s_setprio(1); \
;     _Pragma("unroll") for (int m = 0; m < 4; ++m) _Pragma("unroll") for (int n = 0; n < 2; ++n) _Pragma("unroll") for (int k = 0; k < 2; ++k) \
;       acc[ai][bj][m][n] = __builtin_amdgcn_mfma_f32_16x16x32_bf16(Bt_[n][k], At[m][k], acc[ai][bj][m][n], 0, 0, 0); \
;     __builtin_amdgcn_s_setprio(0); } while (0)
; #define WAIT_V(n) asm volatile("s_waitcnt vmcnt(" #n ")" ::: "memory")
; __device__ __forceinline__ void gemm_phase(KP p, char* shmc, const u16* __restrict__ A,
;                                            const u16* __restrict__ Bt, const int N, const int K, const int mode,
;                                            const float* __restrict__ xin, const float resw) {
;     ...
;       LDB(B1, 0, 1); STAGE(SB(0, 0), Bt, bcol, t + 2);
;       BAR; WAIT_L(0); MMA(0, 1, At, B1); BAR;
;       LDA(At, 0, 1); STAGE(SA(0, 0), A, brow, t + 2);
;       BAR; WAIT_L(0); MMA(1, 0, At, B0); BAR; SCHED;
;       STAGE(SB(0, 1), Bt, bcol + HALF, t + 2);
;       WAIT_V(6); BAR; MMA(1, 1, At, B1); BAR;
;       LDB(B0, 1, 0); SCHED; LDA(At, 1, 0); STAGE(SA(0, 1), A, brow + HALF, t + 2);
;       WAIT_L(8); BAR; WAIT_L(0); MMA(0, 0, At, B0); BAR; SCHED;
;       LDB(B1, 1, 1); STAGE(SB(1, 0), Bt, bcol, t + 3);
;       BAR; WAIT_L(0); MMA(0, 1, At, B1); BAR;
;       LDA(At, 1, 1); STAGE(SA(1, 0), A, brow, t + 3);
;       BAR; WAIT_L(0); MMA(1, 0, At, B0); BAR; SCHED;
;       STAGE(SB(1, 1), Bt, bcol + HALF, t + 3);
;       WAIT_V(6); BAR; MMA(1, 1, At, B1); BAR;
	v_mfma_f32_16x16x32_bf16 v[56:59], v[194:197], v[160:163], v[56:59]
	v_mfma_f32_16x16x32_bf16 v[48:51], v[202:205], v[160:163], v[48:51]
	ds_read_b128 v[128:131], v234 offset:32768
	v_mfma_f32_16x16x32_bf16 v[40:43], v[194:197], v[168:171], v[40:43]
	ds_read_b128 v[132:135], v234 offset:33792
	v_mfma_f32_16x16x32_bf16 v[32:35], v[202:205], v[168:171], v[32:35]
	ds_read_b128 v[136:139], v234 offset:34816
	s_add_u32 m0, s40, 0x4000
	v_mfma_f32_16x16x32_bf16 v[24:27], v[194:197], v[176:179], v[24:27]
	ds_read_b128 v[140:143], v234 offset:35840
	v_mfma_f32_16x16x32_bf16 v[16:19], v[202:205], v[176:179], v[16:19]
	ds_read_b128 v[144:147], v234 offset:36864
	global_load_lds_dwordx4 v236, s[8:9]
	v_mfma_f32_16x16x32_bf16 v[8:11], v[194:197], v[184:187], v[8:11]
	ds_read_b128 v[148:151], v234 offset:37888
	v_mfma_f32_16x16x32_bf16 v[0:3], v[202:205], v[184:187], v[0:3]
	ds_read_b128 v[152:155], v234 offset:38912
	s_add_u32 m0, s40, 0x6000
	v_mfma_f32_16x16x32_bf16 v[56:59], v[198:201], v[164:167], v[56:59]
	ds_read_b128 v[156:159], v234 offset:39936
	v_mfma_f32_16x16x32_bf16 v[48:51], v[206:209], v[164:167], v[48:51]
	global_load_lds_dwordx4 v237, s[8:9]
	v_mfma_f32_16x16x32_bf16 v[40:43], v[198:201], v[172:175], v[40:43]
	v_mfma_f32_16x16x32_bf16 v[32:35], v[206:209], v[172:175], v[32:35]
	s_add_u32 s8, s8, 0x80
	s_addc_u32 s9, s9, 0
	v_mfma_f32_16x16x32_bf16 v[24:27], v[198:201], v[180:183], v[24:27]
	v_mfma_f32_16x16x32_bf16 v[16:19], v[206:209], v[180:183], v[16:19]
	v_mfma_f32_16x16x32_bf16 v[8:11], v[198:201], v[188:191], v[8:11]
	v_mfma_f32_16x16x32_bf16 v[0:3], v[206:209], v[188:191], v[0:3]
	s_waitcnt vmcnt(12) lgkmcnt(0)
	s_barrier
	v_mfma_f32_16x16x32_bf16 v[60:63], v[218:221], v[160:163], v[60:63]
	v_mfma_f32_16x16x32_bf16 v[52:55], v[226:229], v[160:163], v[52:55]
	ds_read_b128 v[194:197], v235 offset:32768
	v_mfma_f32_16x16x32_bf16 v[44:47], v[218:221], v[168:171], v[44:47]
	ds_read_b128 v[198:201], v235 offset:33792
	v_mfma_f32_16x16x32_bf16 v[36:39], v[226:229], v[168:171], v[36:39]
	ds_read_b128 v[202:205], v235 offset:34816
	s_add_u32 m0, s40, 0x8000
	v_mfma_f32_16x16x32_bf16 v[28:31], v[218:221], v[176:179], v[28:31]
	ds_read_b128 v[206:209], v235 offset:35840
	v_mfma_f32_16x16x32_bf16 v[20:23], v[226:229], v[176:179], v[20:23]
	global_load_lds_dwordx4 v236, s[36:37]
	v_mfma_f32_16x16x32_bf16 v[12:15], v[218:221], v[184:187], v[12:15]
	v_mfma_f32_16x16x32_bf16 v[4:7], v[226:229], v[184:187], v[4:7]
	s_add_u32 m0, s40, 0xa000
	v_mfma_f32_16x16x32_bf16 v[60:63], v[222:225], v[164:167], v[60:63]
	v_mfma_f32_16x16x32_bf16 v[52:55], v[230:233], v[164:167], v[52:55]
	global_load_lds_dwordx4 v237, s[36:37]
	v_mfma_f32_16x16x32_bf16 v[44:47], v[222:225], v[172:175], v[44:47]
	v_mfma_f32_16x16x32_bf16 v[36:39], v[230:233], v[172:175], v[36:39]
	s_add_u32 s36, s36, 0x80
	s_addc_u32 s37, s37, 0
	v_mfma_f32_16x16x32_bf16 v[28:31], v[222:225], v[180:183], v[28:31]
	v_mfma_f32_16x16x32_bf16 v[20:23], v[230:233], v[180:183], v[20:23]
	v_mfma_f32_16x16x32_bf16 v[12:15], v[222:225], v[188:191], v[12:15]
	v_mfma_f32_16x16x32_bf16 v[4:7], v[230:233], v[188:191], v[4:7]
	s_waitcnt vmcnt(12) lgkmcnt(0)
	s_barrier
	v_mfma_f32_16x16x32_bf16 v[120:123], v[194:197], v[128:131], v[120:123]
	v_mfma_f32_16x16x32_bf16 v[112:115], v[202:205], v[128:131], v[112:115]
	ds_read_b128 v[218:221], v235 offset:49152
	v_mfma_f32_16x16x32_bf16 v[104:107], v[194:197], v[136:139], v[104:107]
	ds_read_b128 v[222:225], v235 offset:50176
	v_mfma_f32_16x16x32_bf16 v[96:99], v[202:205], v[136:139], v[96:99]
	ds_read_b128 v[226:229], v235 offset:51200
	s_add_u32 m0, s40, 0x18000
	v_mfma_f32_16x16x32_bf16 v[88:91], v[194:197], v[144:147], v[88:91]
	ds_read_b128 v[230:233], v235 offset:52224
	v_mfma_f32_16x16x32_bf16 v[80:83], v[202:205], v[144:147], v[80:83]
	global_load_lds_dwordx4 v236, s[26:27]
	v_mfma_f32_16x16x32_bf16 v[72:75], v[194:197], v[152:155], v[72:75]
	v_mfma_f32_16x16x32_bf16 v[64:67], v[202:205], v[152:155], v[64:67]
	s_add_u32 m0, s40, 0x1a000
	v_mfma_f32_16x16x32_bf16 v[120:123], v[198:201], v[132:135], v[120:123]
	v_mfma_f32_16x16x32_bf16 v[112:115], v[206:209], v[132:135], v[112:115]
	global_load_lds_dwordx4 v237, s[26:27]
	v_mfma_f32_16x16x32_bf16 v[104:107], v[198:201], v[140:143], v[104:107]
	v_mfma_f32_16x16x32_bf16 v[96:99], v[206:209], v[140:143], v[96:99]
	s_add_u32 s26, s26, 0x80
	s_addc_u32 s27, s27, 0
	v_mfma_f32_16x16x32_bf16 v[88:91], v[198:201], v[148:151], v[88:91]
	v_mfma_f32_16x16x32_bf16 v[80:83], v[206:209], v[148:151], v[80:83]
	v_mfma_f32_16x16x32_bf16 v[72:75], v[198:201], v[156:159], v[72:75]
	v_mfma_f32_16x16x32_bf16 v[64:67], v[206:209], v[156:159], v[64:67]
	s_waitcnt vmcnt(12) lgkmcnt(0)
	s_barrier
	v_mfma_f32_16x16x32_bf16 v[124:127], v[218:221], v[128:131], v[124:127]
	v_mfma_f32_16x16x32_bf16 v[116:119], v[226:229], v[128:131], v[116:119]
	ds_read_b128 v[160:163], v234 offset:49152
	v_mfma_f32_16x16x32_bf16 v[108:111], v[218:221], v[136:139], v[108:111]
	ds_read_b128 v[164:167], v234 offset:50176
	v_mfma_f32_16x16x32_bf16 v[100:103], v[226:229], v[136:139], v[100:103]
	ds_read_b128 v[168:171], v234 offset:51200
	s_add_u32 m0, s40, 0x1c000
	v_mfma_f32_16x16x32_bf16 v[92:95], v[218:221], v[144:147], v[92:95]
	ds_read_b128 v[172:175], v234 offset:52224
	v_mfma_f32_16x16x32_bf16 v[84:87], v[226:229], v[144:147], v[84:87]
	ds_read_b128 v[176:179], v234 offset:53248
	global_load_lds_dwordx4 v236, s[38:39]
	v_mfma_f32_16x16x32_bf16 v[76:79], v[218:221], v[152:155], v[76:79]
	ds_read_b128 v[180:183], v234 offset:54272
	v_mfma_f32_16x16x32_bf16 v[68:71], v[226:229], v[152:155], v[68:71]
	ds_read_b128 v[184:187], v234 offset:55296
	s_add_u32 m0, s40, 0x1e000
	v_mfma_f32_16x16x32_bf16 v[124:127], v[222:225], v[132:135], v[124:127]
	ds_read_b128 v[188:191], v234 offset:56320
	v_mfma_f32_16x16x32_bf16 v[116:119], v[230:233], v[132:135], v[116:119]
	global_load_lds_dwordx4 v237, s[38:39]
	v_mfma_f32_16x16x32_bf16 v[108:111], v[222:225], v[140:143], v[108:111]
	v_mfma_f32_16x16x32_bf16 v[100:103], v[230:233], v[140:143], v[100:103]
	s_add_u32 s38, s38, 0x80
	s_addc_u32 s39, s39, 0
	v_mfma_f32_16x16x32_bf16 v[92:95], v[222:225], v[148:151], v[92:95]
	v_mfma_f32_16x16x32_bf16 v[84:87], v[230:233], v[148:151], v[84:87]
	v_mfma_f32_16x16x32_bf16 v[76:79], v[222:225], v[156:159], v[76:79]
	v_mfma_f32_16x16x32_bf16 v[68:71], v[230:233], v[156:159], v[68:71]
	s_waitcnt vmcnt(12) lgkmcnt(0)
	s_barrier
; #define STAGE(P, BASE, br, kt) do { const u16* _gb = (BASE) + ((size_t)(br) * K + (size_t)(kt) * BK); \
;     __builtin_amdgcn_global_load_lds((const unsigned*)(_gb + goff0), (unsigned*)((char*)(P) + tid * 16), 16, 0, 0); \
;     __builtin_amdgcn_global_load_lds((const unsigned*)(_gb + (size_t)64 * K + goff0), (unsigned*)((char*)(P) + tid * 16 + 8192), 16, 0, 0); } while (0)
; #define LDA(dst, b, h) _Pragma("unroll") for (int m = 0; m < 4; ++m) _Pragma("unroll") for (int k = 0; k < 2; ++k) \
;     dst[m][k] = *reinterpret_cast<const bf16x8*>((char*)SA(b, h) + lds_byte(wr * 64 + m * 16 + fr, k * 32 + fq * 8))
; #define LDB(dst, b, h) _Pragma("unroll") for (int n = 0; n < 2; ++n) _Pragma("unroll") for (int k = 0; k < 2; ++k) \
;     dst[n][k] = *reinterpret_cast<const bf16x8*>((char*)SB(b, h) + lds_byte(wc * 32 + n * 16 + fr, k * 32 + fq * 8))
; #define MMA(ai, bj, At, Bt_) do { __builtin_amdgcn_s_setprio(1); \
;     _Pragma("unroll") for (int m = 0; m < 4; ++m) _Pragma("unroll") for (int n = 0; n < 2; ++n) _Pragma("unroll") for (int k = 0; k < 2; ++k) \
;       acc[ai][bj][m][n] = __builtin_amdgcn_mfma_f32_16x16x32_bf16(Bt_[n][k], At[m][k], acc[ai][bj][m][n], 0, 0, 0); \
;     __builtin_amdgcn_s_setprio(0); } while (0)
; #define WAIT_V(n) asm volatile("s_waitcnt vmcnt(" #n ")" ::: "memory")
; #define WAIT_L(n) asm volatile("s_waitcnt lgkmcnt(" #n ")" ::: "memory")
; #define BAR __builtin_amdgcn_s_barrier()
; #define SCHED __builtin_amdgcn_sched_barrier(0)
; __device__ __forceinline__ void gemm_phase(KP p, char* shmc, const u16* __restrict__ A,
;                                            const u16* __restrict__ Bt, const int N, const int K, const int mode,
;                                            const float* __restrict__ xin, const float resw) {
;     ...
;       LDA(At, 1, 1); STAGE(SA(1, 0), A, brow, t + 3);
;       BAR; WAIT_L(0); MMA(1, 0, At, B0); BAR; SCHED;
;       STAGE(SB(1, 1), Bt, bcol + HALF, t + 3);
;       WAIT_V(6); BAR; MMA(1, 1, At, B1); BAR;
;     }
;     { LDB(B0, 0, 0); LDA(At, 0, 0); STAGE(SA(1, 1), A, brow + HALF, nt - 1);
;       BAR; WAIT_L(0); MMA(0, 0, At, B0); BAR;
;       LDB(B1, 0, 1); BAR; WAIT_L(0); MMA(0, 1, At, B1); BAR;
;       LDA(At, 0, 1); WAIT_V(4); BAR; WAIT_L(0); MMA(1, 0, At, B0); MMA(1, 1, At, B1); BAR; }
	v_mfma_f32_16x16x32_bf16 v[56:59], v[194:197], v[160:163], v[56:59]
	v_mfma_f32_16x16x32_bf16 v[48:51], v[202:205], v[160:163], v[48:51]
	ds_read_b128 v[128:131], v234 offset:0
	v_mfma_f32_16x16x32_bf16 v[40:43], v[194:197], v[168:171], v[40:43]
	ds_read_b128 v[132:135], v234 offset:1024
	v_mfma_f32_16x16x32_bf16 v[32:35], v[202:205], v[168:171], v[32:35]
	ds_read_b128 v[136:139], v234 offset:2048
	s_add_u32 m0, s40, 0xc000
	v_mfma_f32_16x16x32_bf16 v[24:27], v[194:197], v[176:179], v[24:27]
	ds_read_b128 v[140:143], v234 offset:3072
	v_mfma_f32_16x16x32_bf16 v[16:19], v[202:205], v[176:179], v[16:19]
	ds_read_b128 v[144:147], v234 offset:4096
	global_load_lds_dwordx4 v236, s[8:9]
	v_mfma_f32_16x16x32_bf16 v[8:11], v[194:197], v[184:187], v[8:11]
	ds_read_b128 v[148:151], v234 offset:5120
	v_mfma_f32_16x16x32_bf16 v[0:3], v[202:205], v[184:187], v[0:3]
	ds_read_b128 v[152:155], v234 offset:6144
	s_add_u32 m0, s40, 0xe000
	v_mfma_f32_16x16x32_bf16 v[56:59], v[198:201], v[164:167], v[56:59]
	ds_read_b128 v[156:159], v234 offset:7168
	v_mfma_f32_16x16x32_bf16 v[48:51], v[206:209], v[164:167], v[48:51]
	global_load_lds_dwordx4 v237, s[8:9]
	v_mfma_f32_16x16x32_bf16 v[40:43], v[198:201], v[172:175], v[40:43]
	v_mfma_f32_16x16x32_bf16 v[32:35], v[206:209], v[172:175], v[32:35]
	s_add_u32 s8, s8, 0x80
	s_addc_u32 s9, s9, 0
	v_mfma_f32_16x16x32_bf16 v[24:27], v[198:201], v[180:183], v[24:27]
	v_mfma_f32_16x16x32_bf16 v[16:19], v[206:209], v[180:183], v[16:19]
	v_mfma_f32_16x16x32_bf16 v[8:11], v[198:201], v[188:191], v[8:11]
	v_mfma_f32_16x16x32_bf16 v[0:3], v[206:209], v[188:191], v[0:3]
	s_waitcnt vmcnt(12) lgkmcnt(0)
	s_barrier
	v_mfma_f32_16x16x32_bf16 v[60:63], v[218:221], v[160:163], v[60:63]
	v_mfma_f32_16x16x32_bf16 v[52:55], v[226:229], v[160:163], v[52:55]
	ds_read_b128 v[194:197], v235 offset:0
	v_mfma_f32_16x16x32_bf16 v[44:47], v[218:221], v[168:171], v[44:47]
	ds_read_b128 v[198:201], v235 offset:1024
	v_mfma_f32_16x16x32_bf16 v[36:39], v[226:229], v[168:171], v[36:39]
	ds_read_b128 v[202:205], v235 offset:2048
	v_mfma_f32_16x16x32_bf16 v[28:31], v[218:221], v[176:179], v[28:31]
	ds_read_b128 v[206:209], v235 offset:3072
	v_mfma_f32_16x16x32_bf16 v[20:23], v[226:229], v[176:179], v[20:23]
	v_mfma_f32_16x16x32_bf16 v[12:15], v[218:221], v[184:187], v[12:15]
	v_mfma_f32_16x16x32_bf16 v[4:7], v[226:229], v[184:187], v[4:7]
	v_mfma_f32_16x16x32_bf16 v[60:63], v[222:225], v[164:167], v[60:63]
	v_mfma_f32_16x16x32_bf16 v[52:55], v[230:233], v[164:167], v[52:55]
	v_mfma_f32_16x16x32_bf16 v[44:47], v[222:225], v[172:175], v[44:47]
	v_mfma_f32_16x16x32_bf16 v[36:39], v[230:233], v[172:175], v[36:39]
	v_mfma_f32_16x16x32_bf16 v[28:31], v[222:225], v[180:183], v[28:31]
	v_mfma_f32_16x16x32_bf16 v[20:23], v[230:233], v[180:183], v[20:23]
	v_mfma_f32_16x16x32_bf16 v[12:15], v[222:225], v[188:191], v[12:15]
	v_mfma_f32_16x16x32_bf16 v[4:7], v[230:233], v[188:191], v[4:7]
	s_waitcnt vmcnt(10) lgkmcnt(0)
	s_barrier
	v_mfma_f32_16x16x32_bf16 v[120:123], v[194:197], v[128:131], v[120:123]
	v_mfma_f32_16x16x32_bf16 v[112:115], v[202:205], v[128:131], v[112:115]
	ds_read_b128 v[218:221], v235 offset:16384
	v_mfma_f32_16x16x32_bf16 v[104:107], v[194:197], v[136:139], v[104:107]
	ds_read_b128 v[222:225], v235 offset:17408
	v_mfma_f32_16x16x32_bf16 v[96:99], v[202:205], v[136:139], v[96:99]
	ds_read_b128 v[226:229], v235 offset:18432
	v_mfma_f32_16x16x32_bf16 v[88:91], v[194:197], v[144:147], v[88:91]
	ds_read_b128 v[230:233], v235 offset:19456
	v_mfma_f32_16x16x32_bf16 v[80:83], v[202:205], v[144:147], v[80:83]
	v_mfma_f32_16x16x32_bf16 v[72:75], v[194:197], v[152:155], v[72:75]
	v_mfma_f32_16x16x32_bf16 v[64:67], v[202:205], v[152:155], v[64:67]
	v_mfma_f32_16x16x32_bf16 v[120:123], v[198:201], v[132:135], v[120:123]
	v_mfma_f32_16x16x32_bf16 v[112:115], v[206:209], v[132:135], v[112:115]
	v_mfma_f32_16x16x32_bf16 v[104:107], v[198:201], v[140:143], v[104:107]
	v_mfma_f32_16x16x32_bf16 v[96:99], v[206:209], v[140:143], v[96:99]
	v_mfma_f32_16x16x32_bf16 v[88:91], v[198:201], v[148:151], v[88:91]
	v_mfma_f32_16x16x32_bf16 v[80:83], v[206:209], v[148:151], v[80:83]
	v_mfma_f32_16x16x32_bf16 v[72:75], v[198:201], v[156:159], v[72:75]
	v_mfma_f32_16x16x32_bf16 v[64:67], v[206:209], v[156:159], v[64:67]
	s_waitcnt vmcnt(8) lgkmcnt(0)
	s_barrier
	v_mfma_f32_16x16x32_bf16 v[124:127], v[218:221], v[128:131], v[124:127]
	v_mfma_f32_16x16x32_bf16 v[116:119], v[226:229], v[128:131], v[116:119]
	ds_read_b128 v[160:163], v234 offset:16384
	v_mfma_f32_16x16x32_bf16 v[108:111], v[218:221], v[136:139], v[108:111]
	ds_read_b128 v[164:167], v234 offset:17408
	v_mfma_f32_16x16x32_bf16 v[100:103], v[226:229], v[136:139], v[100:103]
	ds_read_b128 v[168:171], v234 offset:18432
	v_mfma_f32_16x16x32_bf16 v[92:95], v[218:221], v[144:147], v[92:95]
	ds_read_b128 v[172:175], v234 offset:19456
	v_mfma_f32_16x16x32_bf16 v[84:87], v[226:229], v[144:147], v[84:87]
	ds_read_b128 v[176:179], v234 offset:20480
	v_mfma_f32_16x16x32_bf16 v[76:79], v[218:221], v[152:155], v[76:79]
	ds_read_b128 v[180:183], v234 offset:21504
	v_mfma_f32_16x16x32_bf16 v[68:71], v[226:229], v[152:155], v[68:71]
	ds_read_b128 v[184:187], v234 offset:22528
	v_mfma_f32_16x16x32_bf16 v[124:127], v[222:225], v[132:135], v[124:127]
	ds_read_b128 v[188:191], v234 offset:23552
	v_mfma_f32_16x16x32_bf16 v[116:119], v[230:233], v[132:135], v[116:119]
	v_mfma_f32_16x16x32_bf16 v[108:111], v[222:225], v[140:143], v[108:111]
	v_mfma_f32_16x16x32_bf16 v[100:103], v[230:233], v[140:143], v[100:103]
	v_mfma_f32_16x16x32_bf16 v[92:95], v[222:225], v[148:151], v[92:95]
	v_mfma_f32_16x16x32_bf16 v[84:87], v[230:233], v[148:151], v[84:87]
	v_mfma_f32_16x16x32_bf16 v[76:79], v[222:225], v[156:159], v[76:79]
	v_mfma_f32_16x16x32_bf16 v[68:71], v[230:233], v[156:159], v[68:71]
	s_waitcnt vmcnt(6) lgkmcnt(0)
	s_barrier
; #define STAGE(P, BASE, br, kt) do { const u16* _gb = (BASE) + ((size_t)(br) * K + (size_t)(kt) * BK); \
;     __builtin_amdgcn_global_load_lds((const unsigned*)(_gb + goff0), (unsigned*)((char*)(P) + tid * 16), 16, 0, 0); \
;     __builtin_amdgcn_global_load_lds((const unsigned*)(_gb + (size_t)64 * K + goff0), (unsigned*)((char*)(P) + tid * 16 + 8192), 16, 0, 0); } while (0)
; #define LDA(dst, b, h) _Pragma("unroll") for (int m = 0; m < 4; ++m) _Pragma("unroll") for (int k = 0; k < 2; ++k) \
;     dst[m][k] = *reinterpret_cast<const bf16x8*>((char*)SA(b, h) + lds_byte(wr * 64 + m * 16 + fr, k * 32 + fq * 8))
; #define LDB(dst, b, h) _Pragma("unroll") for (int n = 0; n < 2; ++n) _Pragma("unroll") for (int k = 0; k < 2; ++k) \
;     dst[n][k] = *reinterpret_cast<const bf16x8*>((char*)SB(b, h) + lds_byte(wc * 32 + n * 16 + fr, k * 32 + fq * 8))
; #define MMA(ai, bj, At, Bt_) do { __builtin_amdgcn_s_setprio(1); \
;     _Pragma("unroll") for (int m = 0; m < 4; ++m) _Pragma("unroll") for (int n = 0; n < 2; ++n) _Pragma("unroll") for (int k = 0; k < 2; ++k) \
;       acc[ai][bj][m][n] = __builtin_amdgcn_mfma_f32_16x16x32_bf16(Bt_[n][k], At[m][k], acc[ai][bj][m][n], 0, 0, 0); \
;     __builtin_amdgcn_s_setprio(0); } while (0)
; #define WAIT_V(n) asm volatile("s_waitcnt vmcnt(" #n ")" ::: "memory")
; #define WAIT_L(n) asm volatile("s_waitcnt lgkmcnt(" #n ")" ::: "memory")
; #define BAR __builtin_amdgcn_s_barrier()
; __device__ __forceinline__ void gemm_phase(KP p, char* shmc, const u16* __restrict__ A,
;                                            const u16* __restrict__ Bt, const int N, const int K, const int mode,
;                                            const float* __restrict__ xin, const float resw) {
;     ...
;     { LDB(B0, 0, 0); LDA(At, 0, 0); STAGE(SA(1, 1), A, brow + HALF, nt - 1);
;       BAR; WAIT_L(0); MMA(0, 0, At, B0); BAR;
;       LDB(B1, 0, 1); BAR; WAIT_L(0); MMA(0, 1, At, B1); BAR;
;       LDA(At, 0, 1); WAIT_V(4); BAR; WAIT_L(0); MMA(1, 0, At, B0); MMA(1, 1, At, B1); BAR; }
;     { LDB(B0, 1, 0); LDA(At, 1, 0); WAIT_V(2); BAR; WAIT_L(0); MMA(0, 0, At, B0); BAR;
;       LDB(B1, 1, 1); WAIT_V(0); BAR; WAIT_L(0); MMA(0, 1, At, B1); BAR;
;       LDA(At, 1, 1); BAR; WAIT_L(0); MMA(1, 0, At, B0); MMA(1, 1, At, B1); BAR; }
	v_mfma_f32_16x16x32_bf16 v[56:59], v[194:197], v[160:163], v[56:59]
	v_mfma_f32_16x16x32_bf16 v[48:51], v[202:205], v[160:163], v[48:51]
	ds_read_b128 v[128:131], v234 offset:32768
	v_mfma_f32_16x16x32_bf16 v[40:43], v[194:197], v[168:171], v[40:43]
	ds_read_b128 v[132:135], v234 offset:33792
	v_mfma_f32_16x16x32_bf16 v[32:35], v[202:205], v[168:171], v[32:35]
	ds_read_b128 v[136:139], v234 offset:34816
	v_mfma_f32_16x16x32_bf16 v[24:27], v[194:197], v[176:179], v[24:27]
	ds_read_b128 v[140:143], v234 offset:35840
	v_mfma_f32_16x16x32_bf16 v[16:19], v[202:205], v[176:179], v[16:19]
	ds_read_b128 v[144:147], v234 offset:36864
	v_mfma_f32_16x16x32_bf16 v[8:11], v[194:197], v[184:187], v[8:11]
	ds_read_b128 v[148:151], v234 offset:37888
	v_mfma_f32_16x16x32_bf16 v[0:3], v[202:205], v[184:187], v[0:3]
	ds_read_b128 v[152:155], v234 offset:38912
	v_mfma_f32_16x16x32_bf16 v[56:59], v[198:201], v[164:167], v[56:59]
	ds_read_b128 v[156:159], v234 offset:39936
	v_mfma_f32_16x16x32_bf16 v[48:51], v[206:209], v[164:167], v[48:51]
	v_mfma_f32_16x16x32_bf16 v[40:43], v[198:201], v[172:175], v[40:43]
	v_mfma_f32_16x16x32_bf16 v[32:35], v[206:209], v[172:175], v[32:35]
	v_mfma_f32_16x16x32_bf16 v[24:27], v[198:201], v[180:183], v[24:27]
	v_mfma_f32_16x16x32_bf16 v[16:19], v[206:209], v[180:183], v[16:19]
	v_mfma_f32_16x16x32_bf16 v[8:11], v[198:201], v[188:191], v[8:11]
	v_mfma_f32_16x16x32_bf16 v[0:3], v[206:209], v[188:191], v[0:3]
	s_waitcnt vmcnt(4) lgkmcnt(0)
	s_barrier
	v_mfma_f32_16x16x32_bf16 v[60:63], v[218:221], v[160:163], v[60:63]
	v_mfma_f32_16x16x32_bf16 v[52:55], v[226:229], v[160:163], v[52:55]
	ds_read_b128 v[194:197], v235 offset:32768
	v_mfma_f32_16x16x32_bf16 v[44:47], v[218:221], v[168:171], v[44:47]
	ds_read_b128 v[198:201], v235 offset:33792
	v_mfma_f32_16x16x32_bf16 v[36:39], v[226:229], v[168:171], v[36:39]
	ds_read_b128 v[202:205], v235 offset:34816
	v_mfma_f32_16x16x32_bf16 v[28:31], v[218:221], v[176:179], v[28:31]
	ds_read_b128 v[206:209], v235 offset:35840
	v_mfma_f32_16x16x32_bf16 v[20:23], v[226:229], v[176:179], v[20:23]
	v_mfma_f32_16x16x32_bf16 v[12:15], v[218:221], v[184:187], v[12:15]
	v_mfma_f32_16x16x32_bf16 v[4:7], v[226:229], v[184:187], v[4:7]
	v_mfma_f32_16x16x32_bf16 v[60:63], v[222:225], v[164:167], v[60:63]
	v_mfma_f32_16x16x32_bf16 v[52:55], v[230:233], v[164:167], v[52:55]
	v_mfma_f32_16x16x32_bf16 v[44:47], v[222:225], v[172:175], v[44:47]
	v_mfma_f32_16x16x32_bf16 v[36:39], v[230:233], v[172:175], v[36:39]
	v_mfma_f32_16x16x32_bf16 v[28:31], v[222:225], v[180:183], v[28:31]
	v_mfma_f32_16x16x32_bf16 v[20:23], v[230:233], v[180:183], v[20:23]
	v_mfma_f32_16x16x32_bf16 v[12:15], v[222:225], v[188:191], v[12:15]
	v_mfma_f32_16x16x32_bf16 v[4:7], v[230:233], v[188:191], v[4:7]
	s_waitcnt vmcnt(2) lgkmcnt(0)
	s_barrier
	v_mfma_f32_16x16x32_bf16 v[120:123], v[194:197], v[128:131], v[120:123]
	v_mfma_f32_16x16x32_bf16 v[112:115], v[202:205], v[128:131], v[112:115]
	ds_read_b128 v[218:221], v235 offset:49152
	v_mfma_f32_16x16x32_bf16 v[104:107], v[194:197], v[136:139], v[104:107]
	ds_read_b128 v[222:225], v235 offset:50176
	v_mfma_f32_16x16x32_bf16 v[96:99], v[202:205], v[136:139], v[96:99]
	ds_read_b128 v[226:229], v235 offset:51200
	v_mfma_f32_16x16x32_bf16 v[88:91], v[194:197], v[144:147], v[88:91]
	ds_read_b128 v[230:233], v235 offset:52224
	v_mfma_f32_16x16x32_bf16 v[80:83], v[202:205], v[144:147], v[80:83]
	v_mfma_f32_16x16x32_bf16 v[72:75], v[194:197], v[152:155], v[72:75]
	v_mfma_f32_16x16x32_bf16 v[64:67], v[202:205], v[152:155], v[64:67]
	v_mfma_f32_16x16x32_bf16 v[120:123], v[198:201], v[132:135], v[120:123]
	v_mfma_f32_16x16x32_bf16 v[112:115], v[206:209], v[132:135], v[112:115]
	v_mfma_f32_16x16x32_bf16 v[104:107], v[198:201], v[140:143], v[104:107]
	v_mfma_f32_16x16x32_bf16 v[96:99], v[206:209], v[140:143], v[96:99]
	v_mfma_f32_16x16x32_bf16 v[88:91], v[198:201], v[148:151], v[88:91]
	v_mfma_f32_16x16x32_bf16 v[80:83], v[206:209], v[148:151], v[80:83]
	v_mfma_f32_16x16x32_bf16 v[72:75], v[198:201], v[156:159], v[72:75]
	v_mfma_f32_16x16x32_bf16 v[64:67], v[206:209], v[156:159], v[64:67]
	s_waitcnt vmcnt(0) lgkmcnt(0)
	s_barrier
	v_mfma_f32_16x16x32_bf16 v[124:127], v[218:221], v[128:131], v[124:127]
	v_mfma_f32_16x16x32_bf16 v[116:119], v[226:229], v[128:131], v[116:119]
	ds_read_b128 v[160:163], v234 offset:49152
	v_mfma_f32_16x16x32_bf16 v[108:111], v[218:221], v[136:139], v[108:111]
	ds_read_b128 v[164:167], v234 offset:50176
	v_mfma_f32_16x16x32_bf16 v[100:103], v[226:229], v[136:139], v[100:103]
	ds_read_b128 v[168:171], v234 offset:51200
	v_mfma_f32_16x16x32_bf16 v[92:95], v[218:221], v[144:147], v[92:95]
	ds_read_b128 v[172:175], v234 offset:52224
	v_mfma_f32_16x16x32_bf16 v[84:87], v[226:229], v[144:147], v[84:87]
	ds_read_b128 v[176:179], v234 offset:53248
	v_mfma_f32_16x16x32_bf16 v[76:79], v[218:221], v[152:155], v[76:79]
	ds_read_b128 v[180:183], v234 offset:54272
	v_mfma_f32_16x16x32_bf16 v[68:71], v[226:229], v[152:155], v[68:71]
	ds_read_b128 v[184:187], v234 offset:55296
	v_mfma_f32_16x16x32_bf16 v[124:127], v[222:225], v[132:135], v[124:127]
	ds_read_b128 v[188:191], v234 offset:56320
	v_mfma_f32_16x16x32_bf16 v[116:119], v[230:233], v[132:135], v[116:119]
	v_mfma_f32_16x16x32_bf16 v[108:111], v[222:225], v[140:143], v[108:111]
	v_mfma_f32_16x16x32_bf16 v[100:103], v[230:233], v[140:143], v[100:103]
	v_mfma_f32_16x16x32_bf16 v[92:95], v[222:225], v[148:151], v[92:95]
	v_mfma_f32_16x16x32_bf16 v[84:87], v[230:233], v[148:151], v[84:87]
	v_mfma_f32_16x16x32_bf16 v[76:79], v[222:225], v[156:159], v[76:79]
	v_mfma_f32_16x16x32_bf16 v[68:71], v[230:233], v[156:159], v[68:71]
	s_waitcnt lgkmcnt(0)
	s_barrier
; #define LDA(dst, b, h) _Pragma("unroll") for (int m = 0; m < 4; ++m) _Pragma("unroll") for (int k = 0; k < 2; ++k) \
;     dst[m][k] = *reinterpret_cast<const bf16x8*>((char*)SA(b, h) + lds_byte(wr * 64 + m * 16 + fr, k * 32 + fq * 8))
; #define MMA(ai, bj, At, Bt_) do { __builtin_amdgcn_s_setprio(1); \
;     _Pragma("unroll") for (int m = 0; m < 4; ++m) _Pragma("unroll") for (int n = 0; n < 2; ++n) _Pragma("unroll") for (int k = 0; k < 2; ++k) \
;       acc[ai][bj][m][n] = __builtin_amdgcn_mfma_f32_16x16x32_bf16(Bt_[n][k], At[m][k], acc[ai][bj][m][n], 0, 0, 0); \
;     __builtin_amdgcn_s_setprio(0); } while (0)
; #define WAIT_L(n) asm volatile("s_waitcnt lgkmcnt(" #n ")" ::: "memory")
; #define BAR __builtin_amdgcn_s_barrier()
; #define TILE_PREFETCH(brow_, bcol_, par_) do { \
;     STAGE(SB(0, 0), Bt, bcol_, 0); STAGE(SA(0, 0), A, brow_, 0); \
;     STAGE(SB(0, 1), Bt, (bcol_) + HALF, 0); STAGE(SA(0, 1), A, (brow_) + HALF, 0); \
;     STAGE(SB(1, 0), Bt, bcol_, 1); STAGE(SA(1, 0), A, brow_, 1); STAGE(SB(1, 1), Bt, (bcol_) + HALF, 1); } while (0)
; __device__ __forceinline__ void gemm_phase(KP p, char* shmc, const u16* __restrict__ A,
;                                            const u16* __restrict__ Bt, const int N, const int K, const int mode,
;                                            const float* __restrict__ xin, const float resw) {
;     ...
;       LDA(At, 1, 1); BAR; WAIT_L(0); MMA(1, 0, At, B0); MMA(1, 1, At, B1); BAR; }
;     if (wr == 0) BAR;
;     const int ntix = tix + gridDim.x;
;     int nbrow = 0, nbcol = 0, npn = 0;
;     if (ntix < nwg) {
;       TILE_MAP(ntix, nbrow, nbcol, npn);
;       TILE_PREFETCH(nbrow, nbcol, par ^ 1);
	v_mfma_f32_16x16x32_bf16 v[56:59], v[194:197], v[160:163], v[56:59]
	v_mfma_f32_16x16x32_bf16 v[48:51], v[202:205], v[160:163], v[48:51]
	v_mfma_f32_16x16x32_bf16 v[40:43], v[194:197], v[168:171], v[40:43]
	v_mfma_f32_16x16x32_bf16 v[32:35], v[202:205], v[168:171], v[32:35]
	v_mfma_f32_16x16x32_bf16 v[24:27], v[194:197], v[176:179], v[24:27]
	v_mfma_f32_16x16x32_bf16 v[16:19], v[202:205], v[176:179], v[16:19]
	v_mfma_f32_16x16x32_bf16 v[8:11], v[194:197], v[184:187], v[8:11]
	v_mfma_f32_16x16x32_bf16 v[0:3], v[202:205], v[184:187], v[0:3]
	v_mfma_f32_16x16x32_bf16 v[56:59], v[198:201], v[164:167], v[56:59]
	v_mfma_f32_16x16x32_bf16 v[48:51], v[206:209], v[164:167], v[48:51]
	v_mfma_f32_16x16x32_bf16 v[40:43], v[198:201], v[172:175], v[40:43]
	v_mfma_f32_16x16x32_bf16 v[32:35], v[206:209], v[172:175], v[32:35]
	v_mfma_f32_16x16x32_bf16 v[24:27], v[198:201], v[180:183], v[24:27]
	v_mfma_f32_16x16x32_bf16 v[16:19], v[206:209], v[180:183], v[16:19]
	v_mfma_f32_16x16x32_bf16 v[8:11], v[198:201], v[188:191], v[8:11]
	v_mfma_f32_16x16x32_bf16 v[0:3], v[206:209], v[188:191], v[0:3]
	v_mfma_f32_16x16x32_bf16 v[60:63], v[218:221], v[160:163], v[60:63]
	v_mfma_f32_16x16x32_bf16 v[52:55], v[226:229], v[160:163], v[52:55]
	v_mfma_f32_16x16x32_bf16 v[44:47], v[218:221], v[168:171], v[44:47]
	v_mfma_f32_16x16x32_bf16 v[36:39], v[226:229], v[168:171], v[36:39]
	v_mfma_f32_16x16x32_bf16 v[28:31], v[218:221], v[176:179], v[28:31]
	v_mfma_f32_16x16x32_bf16 v[20:23], v[226:229], v[176:179], v[20:23]
	v_mfma_f32_16x16x32_bf16 v[12:15], v[218:221], v[184:187], v[12:15]
	v_mfma_f32_16x16x32_bf16 v[4:7], v[226:229], v[184:187], v[4:7]
	v_mfma_f32_16x16x32_bf16 v[60:63], v[222:225], v[164:167], v[60:63]
	v_mfma_f32_16x16x32_bf16 v[52:55], v[230:233], v[164:167], v[52:55]
	v_mfma_f32_16x16x32_bf16 v[44:47], v[222:225], v[172:175], v[44:47]
	v_mfma_f32_16x16x32_bf16 v[36:39], v[230:233], v[172:175], v[36:39]
	v_mfma_f32_16x16x32_bf16 v[28:31], v[222:225], v[180:183], v[28:31]
	v_mfma_f32_16x16x32_bf16 v[20:23], v[230:233], v[180:183], v[20:23]
	v_mfma_f32_16x16x32_bf16 v[12:15], v[222:225], v[188:191], v[12:15]
	v_mfma_f32_16x16x32_bf16 v[4:7], v[230:233], v[188:191], v[4:7]
	s_nop 7
	s_nop 7
	s_add_i32 s66, s66, s3
	s_cmp_ge_i32 s66, s51
	s_cselect_b64 s[6:7], -1, 0
	s_mov_b32 s26, 0
	s_and_b64 vcc, exec, s[6:7]
	s_mov_b32 s45, 0
	s_mov_b32 s44, 0
	s_cbranch_vccnz .LBB0_55
	s_ashr_i32 s8, s66, 31
	s_lshr_b32 s8, s8, 29
	s_add_i32 s8, s66, s8
	s_ashr_i32 s9, s8, 3
	s_and_b32 s8, s8, -8
	s_sub_i32 s8, s66, s8
	s_lshr_b32 s26, s8, 31
	s_or_b32 s26, s26, s68
	s_mul_i32 s8, s26, s8
	s_add_i32 s8, s8, s9
	s_abs_i32 s26, s8
	s_mul_hi_u32 s27, s26, s69
	s_mul_i32 s36, s27, s81
	s_sub_i32 s26, s26, s36
	s_ashr_i32 s9, s8, 31
	s_add_i32 s36, s27, 1
	s_sub_i32 s37, s26, s81
	s_cmp_ge_u32 s26, s81
	s_cselect_b32 s27, s36, s27
	s_cselect_b32 s26, s37, s26
	s_add_i32 s36, s27, 1
	s_cmp_ge_u32 s26, s81
	s_cselect_b32 s26, s36, s27
	s_xor_b32 s26, s26, s9
	s_sub_i32 s9, s26, s9
	s_lshl_b32 s26, s9, 2
	s_sub_i32 s27, 64, s26
	s_min_i32 s27, s27, 4
	s_abs_i32 s36, s27
	v_cvt_f32_u32_e32 v130, s36
	s_sub_i32 s38, 0, s36
	s_mul_i32 s9, s9, s81
	s_sub_i32 s8, s8, s9
	v_rcp_iflag_f32_e32 v130, v130
	s_abs_i32 s37, s8
	s_xor_b32 s9, s8, s27
	s_ashr_i32 s9, s9, 31
	v_mul_f32_e32 v130, 0x4f7ffffe, v130
	v_cvt_u32_f32_e32 v130, v130
	s_nop 0
	v_readfirstlane_b32 s39, v130
	s_mul_i32 s38, s38, s39
	s_mul_hi_u32 s38, s39, s38
	s_add_i32 s39, s39, s38
	s_mul_hi_u32 s38, s37, s39
	s_mul_i32 s39, s38, s36
	s_sub_i32 s37, s37, s39
	s_add_i32 s39, s38, 1
	s_sub_i32 s40, s37, s36
	s_cmp_ge_u32 s37, s36
	s_cselect_b32 s38, s39, s38
	s_cselect_b32 s37, s40, s37
	s_add_i32 s39, s38, 1
	s_cmp_ge_u32 s37, s36
	s_cselect_b32 s36, s39, s38
	s_xor_b32 s36, s36, s9
	s_sub_i32 s44, s36, s9
	s_mul_i32 s9, s44, s27
	s_sub_i32 s8, s8, s9
	s_add_i32 s8, s8, s26
	s_lshl_b32 s45, s44, 8
	s_lshl_b32 s26, s8, 8
	s_mul_hi_i32 s9, s45, s50
	s_mul_i32 s8, s45, s50
	s_lshl_b64 s[8:9], s[8:9], 1
	s_add_u32 s8, s14, s8
	s_addc_u32 s9, s15, s9
	s_lshl_b32 s27, s72, 1
	s_mul_hi_i32 s41, s26, s50
	s_mul_i32 s40, s26, s50
	s_lshl_b64 s[40:41], s[40:41], 1
	s_add_u32 s40, s12, s40
	s_addc_u32 s41, s13, s41
	s_add_u32 s42, s8, s27
	s_addc_u32 s43, s9, 0
	s_add_u32 s46, s40, s27
	s_addc_u32 s47, s41, 0
	v_readfirstlane_b32 s27, v238
	s_nop 1
	s_add_u32 m0, s27, 0x10000
	s_nop 0
	global_load_lds_dwordx4 v236, s[8:9]
	s_add_u32 m0, s27, 0x12000
	s_nop 0
	global_load_lds_dwordx4 v237, s[8:9]
	s_add_u32 m0, s27, 0x0
	s_nop 0
	global_load_lds_dwordx4 v236, s[40:41]
	s_add_u32 m0, s27, 0x2000
	s_nop 0
	global_load_lds_dwordx4 v237, s[40:41]
	s_add_u32 m0, s27, 0x14000
	s_nop 0
	global_load_lds_dwordx4 v236, s[42:43]
	s_add_u32 m0, s27, 0x16000
	s_nop 0
	global_load_lds_dwordx4 v237, s[42:43]
	s_add_u32 m0, s27, 0x4000
	s_nop 0
	global_load_lds_dwordx4 v236, s[46:47]
	s_add_u32 m0, s27, 0x6000
	s_nop 0
	global_load_lds_dwordx4 v237, s[46:47]
	s_add_u32 s8, s8, 0x80
	s_addc_u32 s9, s9, 0
	s_add_u32 s40, s40, 0x80
	s_addc_u32 s41, s41, 0
	s_add_u32 s42, s42, 0x80
	s_addc_u32 s43, s43, 0
	s_add_u32 s46, s46, 0x80
	s_addc_u32 s47, s47, 0
	s_add_u32 m0, s27, 0x18000
	s_nop 0
	global_load_lds_dwordx4 v236, s[8:9]
	s_add_u32 m0, s27, 0x1a000
	s_nop 0
	global_load_lds_dwordx4 v237, s[8:9]
	s_add_u32 m0, s27, 0x8000
	s_nop 0
	global_load_lds_dwordx4 v236, s[40:41]
	s_add_u32 m0, s27, 0xa000
	s_nop 0
	global_load_lds_dwordx4 v237, s[40:41]
	s_add_u32 m0, s27, 0x1c000
	s_nop 0
	global_load_lds_dwordx4 v236, s[42:43]
	s_add_u32 m0, s27, 0x1e000
	s_nop 0
	global_load_lds_dwordx4 v237, s[42:43]
	s_add_u32 m0, s27, 0xc000
	s_nop 0
	global_load_lds_dwordx4 v236, s[46:47]
	s_add_u32 m0, s27, 0xe000
	s_nop 0
	global_load_lds_dwordx4 v237, s[46:47]

; __global__ void __launch_bounds__(512, 2) hybrid_megakernel(const Params p_byval) {
;   extern __shared__ __attribute__((aligned(16))) char shmc[];
;   cg::grid_group grid = cg::this_grid();
;   KP p = (KP)__builtin_amdgcn_kernarg_segment_ptr();
	.amdhsa_kernel _Z17hybrid_megakernel6Params
		.amdhsa_group_segment_fixed_size 0
		.amdhsa_private_segment_fixed_size 0
		.amdhsa_kernarg_size 512
		.amdhsa_user_sgpr_count 2
		.amdhsa_user_sgpr_dispatch_ptr 0
		.amdhsa_user_sgpr_queue_ptr 0
		.amdhsa_user_sgpr_kernarg_segment_ptr 1
		.amdhsa_user_sgpr_dispatch_id 0
		.amdhsa_user_sgpr_kernarg_preload_length 0
		.amdhsa_user_sgpr_kernarg_preload_offset 0
		.amdhsa_user_sgpr_private_segment_size 0
		.amdhsa_uses_dynamic_stack 0
		.amdhsa_enable_private_segment 0
		.amdhsa_system_sgpr_workgroup_id_x 1
		.amdhsa_system_sgpr_workgroup_id_y 0
		.amdhsa_system_sgpr_workgroup_id_z 0
		.amdhsa_system_sgpr_workgroup_info 0
		.amdhsa_system_vgpr_workitem_id 2
		.amdhsa_next_free_vgpr 252
		.amdhsa_next_free_sgpr 102
		.amdhsa_accum_offset 252
		.amdhsa_reserve_vcc 1
		.amdhsa_float_round_mode_32 0
		.amdhsa_float_round_mode_16_64 0
		.amdhsa_float_denorm_mode_32 3
		.amdhsa_float_denorm_mode_16_64 3
		.amdhsa_dx10_clamp 1
		.amdhsa_ieee_mode 1
		.amdhsa_fp16_overflow 0
		.amdhsa_tg_split 0
		.amdhsa_exception_fp_ieee_invalid_op 0
		.amdhsa_exception_fp_denorm_src 0
		.amdhsa_exception_fp_ieee_div_zero 0
		.amdhsa_exception_fp_ieee_overflow 0
		.amdhsa_exception_fp_ieee_underflow 0
		.amdhsa_exception_fp_ieee_inexact 0
		.amdhsa_exception_int_div_zero 0
	.end_amdhsa_kernel
